# scan: folded constants (bias/softplus pre-scaled by log2e, expm1 polynomial in log2 units, 1-A*A far branch out of line), gelu constants merged
# speedup vs baseline: 1.0207x; 1.0096x over previous
.Lscan1_unit:
	s_and_b32 s37, s23, 15
	s_cmp_eq_u32 s37, s38
	s_cbranch_scc1 .Lscan1_staged
	s_waitcnt vmcnt(0) lgkmcnt(0)
	s_barrier
	s_lshl_b32 s0, s20, 4
	s_add_i32 s0, s0, s37
	s_mul_i32 s0, s0, 0x4800
	s_add_u32 s44, s16, 0x3688000
	s_addc_u32 s45, s17, 0
	s_add_u32 s44, s44, s0
	s_addc_u32 s45, s45, 0
	v_add_u32_e32 v239, 0, v192
	v_mul_u32_u24_e32 v240, 0xaaab, v239
	v_lshrrev_b32_e32 v240, 19, v240
	v_mul_u32_u24_e32 v241, 12, v240
	v_sub_u32_e32 v241, v239, v241
	v_lshlrev_b32_e32 v241, 4, v241
	v_mul_u32_u24_e32 v242, 0xd0, v240
	v_add_u32_e32 v242, v242, v241
	v_mul_u32_u24_e32 v243, 0xc0, v240
	v_add_u32_e32 v243, v243, v241
	v_cmp_lt_u32_e32 vcc, 95, v240
	s_nop 1
	v_mov_b32_e32 v244, 0x8b800
	v_cndmask_b32_e32 v244, 0, v244, vcc
	v_add_u32_e32 v243, v243, v244
	global_load_dwordx4 v[248:251], v243, s[44:45]
	s_waitcnt vmcnt(0)
	ds_write_b128 v242, v[248:251]
	v_add_u32_e32 v239, 512, v192
	v_mul_u32_u24_e32 v240, 0xaaab, v239
	v_lshrrev_b32_e32 v240, 19, v240
	v_mul_u32_u24_e32 v241, 12, v240
	v_sub_u32_e32 v241, v239, v241
	v_lshlrev_b32_e32 v241, 4, v241
	v_mul_u32_u24_e32 v242, 0xd0, v240
	v_add_u32_e32 v242, v242, v241
	v_mul_u32_u24_e32 v243, 0xc0, v240
	v_add_u32_e32 v243, v243, v241
	v_cmp_lt_u32_e32 vcc, 95, v240
	s_nop 1
	v_mov_b32_e32 v244, 0x8b800
	v_cndmask_b32_e32 v244, 0, v244, vcc
	v_add_u32_e32 v243, v243, v244
	global_load_dwordx4 v[248:251], v243, s[44:45]
	s_waitcnt vmcnt(0)
	ds_write_b128 v242, v[248:251]
	v_add_u32_e32 v239, 1024, v192
	v_mul_u32_u24_e32 v240, 0xaaab, v239
	v_lshrrev_b32_e32 v240, 19, v240
	v_mul_u32_u24_e32 v241, 12, v240
	v_sub_u32_e32 v241, v239, v241
	v_lshlrev_b32_e32 v241, 4, v241
	v_mul_u32_u24_e32 v242, 0xd0, v240
	v_add_u32_e32 v242, v242, v241
	v_mul_u32_u24_e32 v243, 0xc0, v240
	v_add_u32_e32 v243, v243, v241
	v_cmp_lt_u32_e32 vcc, 95, v240
	s_nop 1
	v_mov_b32_e32 v244, 0x8b800
	v_cndmask_b32_e32 v244, 0, v244, vcc
	v_add_u32_e32 v243, v243, v244
	global_load_dwordx4 v[248:251], v243, s[44:45]
	s_waitcnt vmcnt(0)
	ds_write_b128 v242, v[248:251]
	v_add_u32_e32 v239, 1536, v192
	v_mul_u32_u24_e32 v240, 0xaaab, v239
	v_lshrrev_b32_e32 v240, 19, v240
	v_mul_u32_u24_e32 v241, 12, v240
	v_sub_u32_e32 v241, v239, v241
	v_lshlrev_b32_e32 v241, 4, v241
	v_mul_u32_u24_e32 v242, 0xd0, v240
	v_add_u32_e32 v242, v242, v241
	v_mul_u32_u24_e32 v243, 0xc0, v240
	v_add_u32_e32 v243, v243, v241
	v_cmp_lt_u32_e32 vcc, 95, v240
	s_nop 1
	v_mov_b32_e32 v244, 0x8b800
	v_cndmask_b32_e32 v244, 0, v244, vcc
	v_add_u32_e32 v243, v243, v244
	global_load_dwordx4 v[248:251], v243, s[44:45]
	s_waitcnt vmcnt(0)
	ds_write_b128 v242, v[248:251]
	v_add_u32_e32 v239, 2048, v192
	v_mul_u32_u24_e32 v240, 0xaaab, v239
	v_lshrrev_b32_e32 v240, 19, v240
	v_mul_u32_u24_e32 v241, 12, v240
	v_sub_u32_e32 v241, v239, v241
	v_lshlrev_b32_e32 v241, 4, v241
	v_mul_u32_u24_e32 v242, 0xd0, v240
	v_add_u32_e32 v242, v242, v241
	v_mul_u32_u24_e32 v243, 0xc0, v240
	v_add_u32_e32 v243, v243, v241
	v_cmp_lt_u32_e32 vcc, 95, v240
	s_nop 1
	v_mov_b32_e32 v244, 0x8b800
	v_cndmask_b32_e32 v244, 0, v244, vcc
	v_add_u32_e32 v243, v243, v244
	v_cmp_gt_u32_e32 vcc, 0x900, v239
	s_and_saveexec_b64 s[62:63], vcc
	global_load_dwordx4 v[248:251], v243, s[44:45]
	s_waitcnt vmcnt(0)
	ds_write_b128 v242, v[248:251]
	s_mov_b64 exec, s[62:63]
	v_cmp_gt_u32_e32 vcc, 0x60, v192
	s_and_saveexec_b64 s[62:63], vcc
	s_mul_i32 s0, s37, 0x180
	v_lshl_add_u32 v239, v192, 2, s0
	global_load_dword v242, v239, s[12:13]
	global_load_dword v243, v239, s[24:25]
	global_load_dword v244, v239, s[26:27]
	v_lshlrev_b32_e32 v240, 2, v192
	s_waitcnt vmcnt(0)
	v_mul_f32_e32 v242, 0xbfb8aa3b, v242
	v_mul_f32_e32 v243, 0xbfb8aa3b, v243
	ds_write_b32 v240, v242 offset:39936
	ds_write_b32 v240, v243 offset:40320
	v_mul_f32_e32 v244, 0xbfb8aa3b, v244
	v_exp_f32_e32 v244, v244
	s_nop 0
	v_add_f32_e32 v245, 1.0, v244
	v_log_f32_e32 v245, v245
	v_fmamk_f32 v246, v244, 0xbe800000, v194
	v_fma_f32 v246, -v244, v246, 0.5
	v_fma_f32 v246, -v244, v246, 1.0
	v_mul_f32_e32 v246, v244, v246
	v_mul_f32_e32 v247, 0x3f317217, v245
	v_fma_f32 v247, v245, s76, -v247
	v_fmac_f32_e32 v247, 0x3377d1cf, v245
	v_fmac_f32_e32 v247, 0x3f317217, v245
	v_cmp_ngt_f32_e32 vcc, s90, v244
	s_nop 1
	v_cndmask_b32_e32 v246, v246, v247, vcc
	v_mul_f32_e32 v246, 0xc138aa3b, v246
	ds_write_b32 v240, v246 offset:40704
	s_mov_b64 exec, s[62:63]
	s_mov_b32 s38, s37
	s_waitcnt lgkmcnt(0)
	s_barrier
.Lscan1_staged:
	s_lshr_b32 s0, s23, 4
	s_lshl_b32 s0, s0, 3
	s_add_i32 s0, s0, s21
	s_mul_i32 s55, s0, 0x5f5
	s_lshr_b32 s55, s55, 16
	s_mul_i32 s56, s55, 43
	s_sub_i32 s56, s0, s56
	s_mul_i32 s57, s55, 0x810
	s_mul_i32 s39, s56, 48
	s_add_i32 s57, s57, s39
	s_mul_i32 s44, s57, 0x1800
	s_mul_hi_u32 s45, s57, 0x1800
	s_mul_i32 s39, s37, 0xc0
	s_add_i32 s39, s39, 0xc00
	s_add_u32 s44, s44, s39
	s_addc_u32 s45, s45, 0
	s_add_u32 s44, s44, s28
	s_addc_u32 s45, s45, s29
	s_add_u32 s62, s44, 0xffffb800
	s_addc_u32 s63, s45, -1
	global_load_dword v59, v233, s[62:63]
	s_add_u32 s62, s62, 0x1800
	s_addc_u32 s63, s63, 0
	global_load_dword v61, v233, s[62:63]
	s_add_u32 s62, s62, 0x1800
	s_addc_u32 s63, s63, 0
	global_load_dword v63, v233, s[62:63]
	s_mov_b64 s[62:63], s[44:45]
	global_load_dword v66, v233, s[62:63]
	s_add_u32 s62, s62, 0x1800
	s_addc_u32 s63, s63, 0
	global_load_dword v67, v233, s[62:63]
	s_add_u32 s62, s62, 0x1800
	s_addc_u32 s63, s63, 0
	global_load_dword v68, v233, s[62:63]
	s_add_u32 s62, s62, 0x1800
	s_addc_u32 s63, s63, 0
	global_load_dword v69, v233, s[62:63]
	s_add_u32 s62, s62, 0x1800
	s_addc_u32 s63, s63, 0
	global_load_dword v70, v233, s[62:63]
	s_add_u32 s62, s62, 0x1800
	s_addc_u32 s63, s63, 0
	global_load_dword v71, v233, s[62:63]
	s_add_u32 s62, s62, 0x1800
	s_addc_u32 s63, s63, 0
	global_load_dword v72, v233, s[62:63]
	s_add_u32 s62, s62, 0x1800
	s_addc_u32 s63, s63, 0
	global_load_dword v73, v233, s[62:63]
	s_add_u32 s62, s62, 0x1800
	s_addc_u32 s63, s63, 0
	global_load_dword v74, v233, s[62:63]
	s_add_u32 s62, s62, 0x1800
	s_addc_u32 s63, s63, 0
	global_load_dword v75, v233, s[62:63]
	s_add_u32 s62, s62, 0x1800
	s_addc_u32 s63, s63, 0
	global_load_dword v76, v233, s[62:63]
	s_add_u32 s62, s62, 0x1800
	s_addc_u32 s63, s63, 0
	global_load_dword v77, v233, s[62:63]
	s_add_u32 s62, s62, 0x1800
	s_addc_u32 s63, s63, 0
	global_load_dword v78, v233, s[62:63]
	s_add_u32 s62, s62, 0x1800
	s_addc_u32 s63, s63, 0
	global_load_dword v79, v233, s[62:63]
	s_add_u32 s62, s62, 0x1800
	s_addc_u32 s63, s63, 0
	global_load_dword v80, v233, s[62:63]
	s_add_u32 s62, s62, 0x1800
	s_addc_u32 s63, s63, 0
	global_load_dword v81, v233, s[62:63]
	s_add_u32 s62, s62, 0x1800
	s_addc_u32 s63, s63, 0
	s_mov_b64 s[44:45], s[62:63]
	s_mul_i32 s39, s37, 0x180
	s_add_u32 s62, s8, s39
	s_addc_u32 s63, s9, 0
	global_load_dwordx2 v[48:49], v234, s[62:63]
	s_add_u32 s62, s62, 0x1800
	s_addc_u32 s63, s63, 0
	global_load_dwordx2 v[50:51], v234, s[62:63]
	s_add_u32 s62, s62, 0x1800
	s_addc_u32 s63, s63, 0
	global_load_dwordx2 v[52:53], v234, s[62:63]
	s_add_u32 s62, s62, 0x1800
	s_addc_u32 s63, s63, 0
	global_load_dwordx2 v[54:55], v234, s[62:63]
	s_add_u32 s62, s10, s39
	s_addc_u32 s63, s11, 0
	global_load_dwordx2 v[56:57], v234, s[62:63]
	s_mul_i32 s39, s55, 43
	s_add_i32 s39, s39, s56
	s_mul_i32 s39, s39, 0x1800
	s_mul_i32 s0, s37, 0x180
	s_add_i32 s39, s39, s0
	s_add_u32 s62, s30, s39
	s_addc_u32 s63, s31, 0
	v_mov_b32_e32 v0, 0
	v_mov_b32_e32 v24, 1.0
	v_mov_b32_e32 v1, 0
	v_mov_b32_e32 v25, 1.0
	v_mov_b32_e32 v2, 0
	v_mov_b32_e32 v26, 1.0
	v_mov_b32_e32 v3, 0
	v_mov_b32_e32 v27, 1.0
	v_mov_b32_e32 v4, 0
	v_mov_b32_e32 v28, 1.0
	v_mov_b32_e32 v5, 0
	v_mov_b32_e32 v29, 1.0
	v_mov_b32_e32 v6, 0
	v_mov_b32_e32 v30, 1.0
	v_mov_b32_e32 v7, 0
	v_mov_b32_e32 v31, 1.0
	v_mov_b32_e32 v8, 0
	v_mov_b32_e32 v32, 1.0
	v_mov_b32_e32 v9, 0
	v_mov_b32_e32 v33, 1.0
	v_mov_b32_e32 v10, 0
	v_mov_b32_e32 v34, 1.0
	v_mov_b32_e32 v11, 0
	v_mov_b32_e32 v35, 1.0
	v_mov_b32_e32 v12, 0
	v_mov_b32_e32 v36, 1.0
	v_mov_b32_e32 v13, 0
	v_mov_b32_e32 v37, 1.0
	v_mov_b32_e32 v14, 0
	v_mov_b32_e32 v38, 1.0
	v_mov_b32_e32 v15, 0
	v_mov_b32_e32 v39, 1.0
	v_mov_b32_e32 v16, 0
	v_mov_b32_e32 v40, 1.0
	v_mov_b32_e32 v17, 0
	v_mov_b32_e32 v41, 1.0
	v_mov_b32_e32 v18, 0
	v_mov_b32_e32 v42, 1.0
	v_mov_b32_e32 v19, 0
	v_mov_b32_e32 v43, 1.0
	v_mov_b32_e32 v20, 0
	v_mov_b32_e32 v44, 1.0
	v_mov_b32_e32 v21, 0
	v_mov_b32_e32 v45, 1.0
	v_mov_b32_e32 v22, 0
	v_mov_b32_e32 v46, 1.0
	v_mov_b32_e32 v23, 0
	v_mov_b32_e32 v47, 1.0
	s_mov_b64 s[6:7], s[62:63]
	v_mov_b32_e32 v248, 0xbd2ec3ff
	v_mov_b32_e32 v249, 0xbdd2d3e8
	s_waitcnt vmcnt(0)
	s_cmp_eq_u32 s56, 0
	s_cbranch_scc1 .Lscan1_hzero
	v_lshlrev_b32_e32 v58, 16, v59
	v_and_b32_e32 v59, 0xffff0000, v59
	v_lshlrev_b32_e32 v60, 16, v61
	v_and_b32_e32 v61, 0xffff0000, v61
	v_lshlrev_b32_e32 v62, 16, v63
	v_and_b32_e32 v63, 0xffff0000, v63
	s_branch .Lscan1_hdone

.Lscan1_hdone:
	s_mov_b32 s55, 0xbe38aa3b
	s_mov_b32 s64, 0
.Lscan1_sub:
	s_mov_b64 s[62:63], s[44:45]
	global_load_dword v82, v233, s[62:63]
	s_add_u32 s62, s62, 0x1800
	s_addc_u32 s63, s63, 0
	global_load_dword v83, v233, s[62:63]
	s_add_u32 s62, s62, 0x1800
	s_addc_u32 s63, s63, 0
	global_load_dword v84, v233, s[62:63]
	s_add_u32 s62, s62, 0x1800
	s_addc_u32 s63, s63, 0
	global_load_dword v85, v233, s[62:63]
	s_add_u32 s62, s62, 0x1800
	s_addc_u32 s63, s63, 0
	global_load_dword v86, v233, s[62:63]
	s_add_u32 s62, s62, 0x1800
	s_addc_u32 s63, s63, 0
	global_load_dword v87, v233, s[62:63]
	s_add_u32 s62, s62, 0x1800
	s_addc_u32 s63, s63, 0
	global_load_dword v88, v233, s[62:63]
	s_add_u32 s62, s62, 0x1800
	s_addc_u32 s63, s63, 0
	global_load_dword v89, v233, s[62:63]
	s_add_u32 s62, s62, 0x1800
	s_addc_u32 s63, s63, 0
	global_load_dword v90, v233, s[62:63]
	s_add_u32 s62, s62, 0x1800
	s_addc_u32 s63, s63, 0
	global_load_dword v91, v233, s[62:63]
	s_add_u32 s62, s62, 0x1800
	s_addc_u32 s63, s63, 0
	global_load_dword v92, v233, s[62:63]
	s_add_u32 s62, s62, 0x1800
	s_addc_u32 s63, s63, 0
	global_load_dword v93, v233, s[62:63]
	s_add_u32 s62, s62, 0x1800
	s_addc_u32 s63, s63, 0
	global_load_dword v94, v233, s[62:63]
	s_add_u32 s62, s62, 0x1800
	s_addc_u32 s63, s63, 0
	global_load_dword v95, v233, s[62:63]
	s_add_u32 s62, s62, 0x1800
	s_addc_u32 s63, s63, 0
	global_load_dword v96, v233, s[62:63]
	s_add_u32 s62, s62, 0x1800
	s_addc_u32 s63, s63, 0
	global_load_dword v97, v233, s[62:63]
	s_add_u32 s62, s62, 0x1800
	s_addc_u32 s63, s63, 0
	s_mov_b64 s[44:45], s[62:63]
	s_mov_b32 s62, -1
	s_mov_b32 s63, 0xffff
	s_mov_b64 exec, s[62:63]
	v_lshlrev_b32_e32 v64, 16, v66
	v_and_b32_e32 v65, 0xffff0000, v66
	v_fma_f32 v242, v58, v48, v56
	v_fma_f32 v243, v59, v49, v57
	v_lshlrev_b32_e32 v58, 16, v67
	v_and_b32_e32 v59, 0xffff0000, v67
	v_fma_f32 v244, v60, v48, v56
	v_fma_f32 v245, v61, v49, v57
	v_fma_f32 v242, v60, v50, v242
	v_fma_f32 v243, v61, v51, v243
	v_fma_f32 v244, v62, v50, v244
	v_fma_f32 v245, v63, v51, v245
	v_fma_f32 v242, v62, v52, v242
	v_fma_f32 v243, v63, v53, v243
	v_fma_f32 v244, v64, v52, v244
	v_fma_f32 v245, v65, v53, v245
	v_fma_f32 v242, v64, v54, v242
	v_fma_f32 v243, v65, v55, v243
	v_fma_f32 v244, v58, v54, v244
	v_fma_f32 v245, v59, v55, v245
	ds_write_b64 v226, v[242:243] offset:0
	v_cvt_pk_bf16_f32 v246, v242, v243
	ds_write_b64 v226, v[244:245] offset:400
	v_cvt_pk_bf16_f32 v247, v244, v245
	ds_write_b32 v227, v246 offset:0
	ds_write_b32 v227, v247 offset:208
	v_lshlrev_b32_e32 v60, 16, v68
	v_and_b32_e32 v61, 0xffff0000, v68
	v_fma_f32 v242, v62, v48, v56
	v_fma_f32 v243, v63, v49, v57
	v_lshlrev_b32_e32 v62, 16, v69
	v_and_b32_e32 v63, 0xffff0000, v69
	v_fma_f32 v244, v64, v48, v56
	v_fma_f32 v245, v65, v49, v57
	v_fma_f32 v242, v64, v50, v242
	v_fma_f32 v243, v65, v51, v243
	v_fma_f32 v244, v58, v50, v244
	v_fma_f32 v245, v59, v51, v245
	v_fma_f32 v242, v58, v52, v242
	v_fma_f32 v243, v59, v53, v243
	v_fma_f32 v244, v60, v52, v244
	v_fma_f32 v245, v61, v53, v245
	v_fma_f32 v242, v60, v54, v242
	v_fma_f32 v243, v61, v55, v243
	v_fma_f32 v244, v62, v54, v244
	v_fma_f32 v245, v63, v55, v245
	ds_write_b64 v226, v[242:243] offset:800
	v_cvt_pk_bf16_f32 v246, v242, v243
	ds_write_b64 v226, v[244:245] offset:1200
	v_cvt_pk_bf16_f32 v247, v244, v245
	ds_write_b32 v227, v246 offset:416
	ds_write_b32 v227, v247 offset:624
	v_lshlrev_b32_e32 v64, 16, v70
	v_and_b32_e32 v65, 0xffff0000, v70
	v_fma_f32 v242, v58, v48, v56
	v_fma_f32 v243, v59, v49, v57
	v_lshlrev_b32_e32 v58, 16, v71
	v_and_b32_e32 v59, 0xffff0000, v71
	v_fma_f32 v244, v60, v48, v56
	v_fma_f32 v245, v61, v49, v57
	v_fma_f32 v242, v60, v50, v242
	v_fma_f32 v243, v61, v51, v243
	v_fma_f32 v244, v62, v50, v244
	v_fma_f32 v245, v63, v51, v245
	v_fma_f32 v242, v62, v52, v242
	v_fma_f32 v243, v63, v53, v243
	v_fma_f32 v244, v64, v52, v244
	v_fma_f32 v245, v65, v53, v245
	v_fma_f32 v242, v64, v54, v242
	v_fma_f32 v243, v65, v55, v243
	v_fma_f32 v244, v58, v54, v244
	v_fma_f32 v245, v59, v55, v245
	ds_write_b64 v226, v[242:243] offset:1600
	v_cvt_pk_bf16_f32 v246, v242, v243
	ds_write_b64 v226, v[244:245] offset:2000
	v_cvt_pk_bf16_f32 v247, v244, v245
	ds_write_b32 v227, v246 offset:832
	ds_write_b32 v227, v247 offset:1040
	v_lshlrev_b32_e32 v60, 16, v72
	v_and_b32_e32 v61, 0xffff0000, v72
	v_fma_f32 v242, v62, v48, v56
	v_fma_f32 v243, v63, v49, v57
	v_lshlrev_b32_e32 v62, 16, v73
	v_and_b32_e32 v63, 0xffff0000, v73
	v_fma_f32 v244, v64, v48, v56
	v_fma_f32 v245, v65, v49, v57
	v_fma_f32 v242, v64, v50, v242
	v_fma_f32 v243, v65, v51, v243
	v_fma_f32 v244, v58, v50, v244
	v_fma_f32 v245, v59, v51, v245
	v_fma_f32 v242, v58, v52, v242
	v_fma_f32 v243, v59, v53, v243
	v_fma_f32 v244, v60, v52, v244
	v_fma_f32 v245, v61, v53, v245
	v_fma_f32 v242, v60, v54, v242
	v_fma_f32 v243, v61, v55, v243
	v_fma_f32 v244, v62, v54, v244
	v_fma_f32 v245, v63, v55, v245
	ds_write_b64 v226, v[242:243] offset:2400
	v_cvt_pk_bf16_f32 v246, v242, v243
	ds_write_b64 v226, v[244:245] offset:2800
	v_cvt_pk_bf16_f32 v247, v244, v245
	ds_write_b32 v227, v246 offset:1248
	ds_write_b32 v227, v247 offset:1456
	v_lshlrev_b32_e32 v64, 16, v74
	v_and_b32_e32 v65, 0xffff0000, v74
	v_fma_f32 v242, v58, v48, v56
	v_fma_f32 v243, v59, v49, v57
	v_lshlrev_b32_e32 v58, 16, v75
	v_and_b32_e32 v59, 0xffff0000, v75
	v_fma_f32 v244, v60, v48, v56
	v_fma_f32 v245, v61, v49, v57
	v_fma_f32 v242, v60, v50, v242
	v_fma_f32 v243, v61, v51, v243
	v_fma_f32 v244, v62, v50, v244
	v_fma_f32 v245, v63, v51, v245
	v_fma_f32 v242, v62, v52, v242
	v_fma_f32 v243, v63, v53, v243
	v_fma_f32 v244, v64, v52, v244
	v_fma_f32 v245, v65, v53, v245
	v_fma_f32 v242, v64, v54, v242
	v_fma_f32 v243, v65, v55, v243
	v_fma_f32 v244, v58, v54, v244
	v_fma_f32 v245, v59, v55, v245
	ds_write_b64 v226, v[242:243] offset:3200
	v_cvt_pk_bf16_f32 v246, v242, v243
	ds_write_b64 v226, v[244:245] offset:3600
	v_cvt_pk_bf16_f32 v247, v244, v245
	ds_write_b32 v227, v246 offset:1664
	ds_write_b32 v227, v247 offset:1872
	v_lshlrev_b32_e32 v60, 16, v76
	v_and_b32_e32 v61, 0xffff0000, v76
	v_fma_f32 v242, v62, v48, v56
	v_fma_f32 v243, v63, v49, v57
	v_lshlrev_b32_e32 v62, 16, v77
	v_and_b32_e32 v63, 0xffff0000, v77
	v_fma_f32 v244, v64, v48, v56
	v_fma_f32 v245, v65, v49, v57
	v_fma_f32 v242, v64, v50, v242
	v_fma_f32 v243, v65, v51, v243
	v_fma_f32 v244, v58, v50, v244
	v_fma_f32 v245, v59, v51, v245
	v_fma_f32 v242, v58, v52, v242
	v_fma_f32 v243, v59, v53, v243
	v_fma_f32 v244, v60, v52, v244
	v_fma_f32 v245, v61, v53, v245
	v_fma_f32 v242, v60, v54, v242
	v_fma_f32 v243, v61, v55, v243
	v_fma_f32 v244, v62, v54, v244
	v_fma_f32 v245, v63, v55, v245
	ds_write_b64 v226, v[242:243] offset:4000
	v_cvt_pk_bf16_f32 v246, v242, v243
	ds_write_b64 v226, v[244:245] offset:4400
	v_cvt_pk_bf16_f32 v247, v244, v245
	ds_write_b32 v227, v246 offset:2080
	ds_write_b32 v227, v247 offset:2288
	v_lshlrev_b32_e32 v64, 16, v78
	v_and_b32_e32 v65, 0xffff0000, v78
	v_fma_f32 v242, v58, v48, v56
	v_fma_f32 v243, v59, v49, v57
	v_lshlrev_b32_e32 v58, 16, v79
	v_and_b32_e32 v59, 0xffff0000, v79
	v_fma_f32 v244, v60, v48, v56
	v_fma_f32 v245, v61, v49, v57
	v_fma_f32 v242, v60, v50, v242
	v_fma_f32 v243, v61, v51, v243
	v_fma_f32 v244, v62, v50, v244
	v_fma_f32 v245, v63, v51, v245
	v_fma_f32 v242, v62, v52, v242
	v_fma_f32 v243, v63, v53, v243
	v_fma_f32 v244, v64, v52, v244
	v_fma_f32 v245, v65, v53, v245
	v_fma_f32 v242, v64, v54, v242
	v_fma_f32 v243, v65, v55, v243
	v_fma_f32 v244, v58, v54, v244
	v_fma_f32 v245, v59, v55, v245
	ds_write_b64 v226, v[242:243] offset:4800
	v_cvt_pk_bf16_f32 v246, v242, v243
	ds_write_b64 v226, v[244:245] offset:5200
	v_cvt_pk_bf16_f32 v247, v244, v245
	ds_write_b32 v227, v246 offset:2496
	ds_write_b32 v227, v247 offset:2704
	v_lshlrev_b32_e32 v60, 16, v80
	v_and_b32_e32 v61, 0xffff0000, v80
	v_fma_f32 v242, v62, v48, v56
	v_fma_f32 v243, v63, v49, v57
	v_lshlrev_b32_e32 v62, 16, v81
	v_and_b32_e32 v63, 0xffff0000, v81
	v_fma_f32 v244, v64, v48, v56
	v_fma_f32 v245, v65, v49, v57
	v_fma_f32 v242, v64, v50, v242
	v_fma_f32 v243, v65, v51, v243
	v_fma_f32 v244, v58, v50, v244
	v_fma_f32 v245, v59, v51, v245
	v_fma_f32 v242, v58, v52, v242
	v_fma_f32 v243, v59, v53, v243
	v_fma_f32 v244, v60, v52, v244
	v_fma_f32 v245, v61, v53, v245
	v_fma_f32 v242, v60, v54, v242
	v_fma_f32 v243, v61, v55, v243
	v_fma_f32 v244, v62, v54, v244
	v_fma_f32 v245, v63, v55, v245
	ds_write_b64 v226, v[242:243] offset:5600
	v_cvt_pk_bf16_f32 v246, v242, v243
	ds_write_b64 v226, v[244:245] offset:6000
	v_cvt_pk_bf16_f32 v247, v244, v245
	ds_write_b32 v227, v246 offset:2912
	ds_write_b32 v227, v247 offset:3120
	s_mov_b64 exec, -1
	s_waitcnt lgkmcnt(0)
	ds_read_b128 v[98:101], v228 offset:0
	ds_read_b128 v[102:105], v228 offset:64
	ds_read_b128 v[106:109], v228 offset:128
	ds_read_b128 v[110:113], v229 offset:0
	ds_read_b128 v[122:125], v229 offset:19968
	ds_read_b128 v[114:117], v229 offset:64
	ds_read_b128 v[126:129], v229 offset:20032
	ds_read_b128 v[118:121], v229 offset:128
	ds_read_b128 v[130:133], v229 offset:20096
	ds_read_b128 v[150:153], v230 offset:0
	ds_read_b128 v[154:157], v230 offset:384
	ds_read_b128 v[158:161], v230 offset:768
	ds_read_b128 v[162:165], v231 offset:0
	s_waitcnt lgkmcnt(0)
	v_mfma_f32_16x16x32_bf16 v[134:137], v[110:113], v[98:101], 0
	v_mfma_f32_16x16x32_bf16 v[138:141], v[122:125], v[98:101], 0
	v_mfma_f32_16x16x32_bf16 v[134:137], v[114:117], v[102:105], v[134:137]
	v_mfma_f32_16x16x32_bf16 v[138:141], v[126:129], v[102:105], v[138:141]
	v_mfma_f32_16x16x32_bf16 v[134:137], v[118:121], v[106:109], v[134:137]
	v_mfma_f32_16x16x32_bf16 v[138:141], v[130:133], v[106:109], v[138:141]
	ds_read_b128 v[110:113], v229 offset:3328
	ds_read_b128 v[122:125], v229 offset:23296
	ds_read_b128 v[114:117], v229 offset:3392
	ds_read_b128 v[126:129], v229 offset:23360
	ds_read_b128 v[118:121], v229 offset:3456
	ds_read_b128 v[130:133], v229 offset:23424
	s_nop 7
	s_nop 7
	v_fmamk_f32 v166, v134, 0xbfb8aa3b, v150
	v_fmamk_f32 v204, v135, 0xbfb8aa3b, v151
	v_fmamk_f32 v210, v136, 0xbfb8aa3b, v152
	v_fmamk_f32 v216, v137, 0xbfb8aa3b, v153
	v_fmamk_f32 v167, v138, 0xbfb8aa3b, v154
	v_fmamk_f32 v205, v139, 0xbfb8aa3b, v155
	v_fmamk_f32 v211, v140, 0xbfb8aa3b, v156
	v_fmamk_f32 v217, v141, 0xbfb8aa3b, v157
	v_exp_f32_e32 v166, v166
	v_exp_f32_e32 v204, v204
	v_exp_f32_e32 v210, v210
	v_exp_f32_e32 v216, v216
	v_exp_f32_e32 v167, v167
	v_exp_f32_e32 v205, v205
	v_exp_f32_e32 v211, v211
	v_exp_f32_e32 v217, v217
	v_add_f32_e32 v166, 1.0, v166
	v_add_f32_e32 v204, 1.0, v204
	v_add_f32_e32 v210, 1.0, v210
	v_add_f32_e32 v216, 1.0, v216
	v_add_f32_e32 v167, 1.0, v167
	v_add_f32_e32 v205, 1.0, v205
	v_add_f32_e32 v211, 1.0, v211
	v_add_f32_e32 v217, 1.0, v217
	v_rcp_f32_e32 v166, v166
	v_rcp_f32_e32 v204, v204
	v_rcp_f32_e32 v210, v210
	v_rcp_f32_e32 v216, v216
	v_rcp_f32_e32 v167, v167
	v_rcp_f32_e32 v205, v205
	v_rcp_f32_e32 v211, v211
	v_rcp_f32_e32 v217, v217
	v_mul_f32_e32 v168, v158, v166
	v_mul_f32_e32 v206, v159, v204
	v_mul_f32_e32 v212, v160, v210
	v_mul_f32_e32 v218, v161, v216
	v_mul_f32_e32 v167, v162, v167
	v_mul_f32_e32 v205, v163, v205
	v_mul_f32_e32 v211, v164, v211
	v_mul_f32_e32 v217, v165, v217
	v_exp_f32_e32 v166, v168
	v_exp_f32_e32 v204, v206
	v_exp_f32_e32 v210, v212
	v_exp_f32_e32 v216, v218
	v_fmaak_f32 v170, v168, v248, 0xbe1d955b
	v_fmaak_f32 v208, v206, v248, 0xbe1d955b
	v_fmaak_f32 v214, v212, v248, 0xbe1d955b
	v_fmaak_f32 v220, v218, v248, 0xbe1d955b
	v_fmaak_f32 v170, v168, v170, 0xbee35847
	v_fmaak_f32 v208, v206, v208, 0xbee35847
	v_fmaak_f32 v214, v212, v214, 0xbee35847
	v_fmaak_f32 v220, v218, v220, 0xbee35847
	v_min3_f32 v169, v168, v206, v212
	v_fmaak_f32 v170, v168, v170, 0xbf75fdf0
	v_fmaak_f32 v208, v206, v208, 0xbf75fdf0
	v_fmaak_f32 v214, v212, v214, 0xbf75fdf0
	v_fmaak_f32 v220, v218, v220, 0xbf75fdf0
	v_min_f32_e32 v169, v169, v218
	v_fmaak_f32 v170, v168, v170, 0xbfb17218
	v_fmaak_f32 v208, v206, v208, 0xbfb17218
	v_fmaak_f32 v214, v212, v214, 0xbfb17218
	v_fmaak_f32 v220, v218, v220, 0xbfb17218
	v_cmp_nlt_f32_e32 vcc, 0xbe38aa3b, v169
	v_mul_f32_e32 v170, v170, v168
	v_mul_f32_e32 v208, v208, v206
	v_mul_f32_e32 v214, v214, v212
	v_mul_f32_e32 v220, v220, v218
	s_cbranch_vccnz .Lscan1_far0
.Lscan1_back0:
	v_sqrt_f32_e32 v170, v170
	v_sqrt_f32_e32 v208, v208
	v_sqrt_f32_e32 v214, v214
	v_sqrt_f32_e32 v220, v220
	v_mul_f32_e32 v167, v167, v170
	v_mul_f32_e32 v205, v205, v208
	v_mul_f32_e32 v211, v211, v214
	v_mul_f32_e32 v217, v217, v220
	ds_read_b128 v[150:153], v230 offset:64
	ds_read_b128 v[154:157], v230 offset:448
	ds_read_b128 v[158:161], v230 offset:832
	ds_read_b128 v[162:165], v231 offset:64
	s_waitcnt lgkmcnt(0)
	v_mfma_f32_16x16x32_bf16 v[142:145], v[110:113], v[98:101], 0
	v_mfma_f32_16x16x32_bf16 v[146:149], v[122:125], v[98:101], 0
	v_mfma_f32_16x16x32_bf16 v[142:145], v[114:117], v[102:105], v[142:145]
	v_mfma_f32_16x16x32_bf16 v[146:149], v[126:129], v[102:105], v[146:149]
	v_mfma_f32_16x16x32_bf16 v[142:145], v[118:121], v[106:109], v[142:145]
	v_mfma_f32_16x16x32_bf16 v[146:149], v[130:133], v[106:109], v[146:149]
	v_fmac_f32_dpp v167, v167, v166 row_shr:1 row_mask:0xf bank_mask:0xf bound_ctrl:1
	v_fmac_f32_dpp v205, v205, v204 row_shr:1 row_mask:0xf bank_mask:0xf bound_ctrl:1
	v_fmac_f32_dpp v211, v211, v210 row_shr:1 row_mask:0xf bank_mask:0xf bound_ctrl:1
	v_fmac_f32_dpp v217, v217, v216 row_shr:1 row_mask:0xf bank_mask:0xf bound_ctrl:1
	v_mul_f32_dpp v166, v166, v166 row_shr:1 row_mask:0xf bank_mask:0xf
	v_mul_f32_dpp v204, v204, v204 row_shr:1 row_mask:0xf bank_mask:0xf
	v_mul_f32_dpp v210, v210, v210 row_shr:1 row_mask:0xf bank_mask:0xf
	v_mul_f32_dpp v216, v216, v216 row_shr:1 row_mask:0xf bank_mask:0xf
	v_fmac_f32_dpp v167, v167, v166 row_shr:2 row_mask:0xf bank_mask:0xf bound_ctrl:1
	v_fmac_f32_dpp v205, v205, v204 row_shr:2 row_mask:0xf bank_mask:0xf bound_ctrl:1
	v_fmac_f32_dpp v211, v211, v210 row_shr:2 row_mask:0xf bank_mask:0xf bound_ctrl:1
	v_fmac_f32_dpp v217, v217, v216 row_shr:2 row_mask:0xf bank_mask:0xf bound_ctrl:1
	v_mul_f32_dpp v166, v166, v166 row_shr:2 row_mask:0xf bank_mask:0xf
	v_mul_f32_dpp v204, v204, v204 row_shr:2 row_mask:0xf bank_mask:0xf
	v_mul_f32_dpp v210, v210, v210 row_shr:2 row_mask:0xf bank_mask:0xf
	v_mul_f32_dpp v216, v216, v216 row_shr:2 row_mask:0xf bank_mask:0xf
	v_fmac_f32_dpp v167, v167, v166 row_shr:4 row_mask:0xf bank_mask:0xf bound_ctrl:1
	v_fmac_f32_dpp v205, v205, v204 row_shr:4 row_mask:0xf bank_mask:0xf bound_ctrl:1
	v_fmac_f32_dpp v211, v211, v210 row_shr:4 row_mask:0xf bank_mask:0xf bound_ctrl:1
	v_fmac_f32_dpp v217, v217, v216 row_shr:4 row_mask:0xf bank_mask:0xf bound_ctrl:1
	v_mul_f32_dpp v166, v166, v166 row_shr:4 row_mask:0xf bank_mask:0xf
	v_mul_f32_dpp v204, v204, v204 row_shr:4 row_mask:0xf bank_mask:0xf
	v_mul_f32_dpp v210, v210, v210 row_shr:4 row_mask:0xf bank_mask:0xf
	v_mul_f32_dpp v216, v216, v216 row_shr:4 row_mask:0xf bank_mask:0xf
	v_fmac_f32_dpp v167, v167, v166 row_shr:8 row_mask:0xf bank_mask:0xf bound_ctrl:1
	v_fmac_f32_dpp v205, v205, v204 row_shr:8 row_mask:0xf bank_mask:0xf bound_ctrl:1
	v_fmac_f32_dpp v211, v211, v210 row_shr:8 row_mask:0xf bank_mask:0xf bound_ctrl:1
	v_fmac_f32_dpp v217, v217, v216 row_shr:8 row_mask:0xf bank_mask:0xf bound_ctrl:1
	v_mul_f32_dpp v166, v166, v166 row_shr:8 row_mask:0xf bank_mask:0xf
	v_mul_f32_dpp v204, v204, v204 row_shr:8 row_mask:0xf bank_mask:0xf
	v_mul_f32_dpp v210, v210, v210 row_shr:8 row_mask:0xf bank_mask:0xf
	v_mul_f32_dpp v216, v216, v216 row_shr:8 row_mask:0xf bank_mask:0xf
	v_fma_f32 v168, v166, v0, v167
	v_fma_f32 v206, v204, v1, v205
	v_fma_f32 v212, v210, v2, v211
	v_fma_f32 v218, v216, v3, v217
	ds_bpermute_b32 v0, v232, v168
	ds_bpermute_b32 v1, v232, v206
	ds_bpermute_b32 v2, v232, v212
	ds_bpermute_b32 v3, v232, v218
	ds_bpermute_b32 v222, v232, v166
	ds_bpermute_b32 v223, v232, v204
	ds_bpermute_b32 v224, v232, v210
	ds_bpermute_b32 v225, v232, v216
	ds_read_b128 v[110:113], v229 offset:6656
	ds_read_b128 v[122:125], v229 offset:26624
	ds_read_b128 v[114:117], v229 offset:6720
	ds_read_b128 v[126:129], v229 offset:26688
	ds_read_b128 v[118:121], v229 offset:6784
	ds_read_b128 v[130:133], v229 offset:26752
	v_fmamk_f32 v166, v142, 0xbfb8aa3b, v150
	v_fmamk_f32 v204, v143, 0xbfb8aa3b, v151
	v_fmamk_f32 v210, v144, 0xbfb8aa3b, v152
	v_fmamk_f32 v216, v145, 0xbfb8aa3b, v153
	v_fmamk_f32 v167, v146, 0xbfb8aa3b, v154
	v_fmamk_f32 v205, v147, 0xbfb8aa3b, v155
	v_fmamk_f32 v211, v148, 0xbfb8aa3b, v156
	v_fmamk_f32 v217, v149, 0xbfb8aa3b, v157
	v_exp_f32_e32 v166, v166
	v_exp_f32_e32 v204, v204
	v_exp_f32_e32 v210, v210
	v_exp_f32_e32 v216, v216
	v_exp_f32_e32 v167, v167
	v_exp_f32_e32 v205, v205
	v_exp_f32_e32 v211, v211
	v_exp_f32_e32 v217, v217
	v_add_f32_e32 v166, 1.0, v166
	v_add_f32_e32 v204, 1.0, v204
	v_add_f32_e32 v210, 1.0, v210
	v_add_f32_e32 v216, 1.0, v216
	v_add_f32_e32 v167, 1.0, v167
	v_add_f32_e32 v205, 1.0, v205
	v_add_f32_e32 v211, 1.0, v211
	v_add_f32_e32 v217, 1.0, v217
	v_rcp_f32_e32 v166, v166
	v_rcp_f32_e32 v204, v204
	v_rcp_f32_e32 v210, v210
	v_rcp_f32_e32 v216, v216
	v_rcp_f32_e32 v167, v167
	v_rcp_f32_e32 v205, v205
	v_rcp_f32_e32 v211, v211
	v_rcp_f32_e32 v217, v217
	v_mul_f32_e32 v168, v158, v166
	v_mul_f32_e32 v206, v159, v204
	v_mul_f32_e32 v212, v160, v210
	v_mul_f32_e32 v218, v161, v216
	v_mul_f32_e32 v167, v162, v167
	v_mul_f32_e32 v205, v163, v205
	v_mul_f32_e32 v211, v164, v211
	v_mul_f32_e32 v217, v165, v217
	v_exp_f32_e32 v166, v168
	v_exp_f32_e32 v204, v206
	v_exp_f32_e32 v210, v212
	v_exp_f32_e32 v216, v218
	v_fmaak_f32 v170, v168, v248, 0xbe1d955b
	v_fmaak_f32 v208, v206, v248, 0xbe1d955b
	v_fmaak_f32 v214, v212, v248, 0xbe1d955b
	v_fmaak_f32 v220, v218, v248, 0xbe1d955b
	v_fmaak_f32 v170, v168, v170, 0xbee35847
	v_fmaak_f32 v208, v206, v208, 0xbee35847
	v_fmaak_f32 v214, v212, v214, 0xbee35847
	v_fmaak_f32 v220, v218, v220, 0xbee35847
	v_min3_f32 v169, v168, v206, v212
	v_fmaak_f32 v170, v168, v170, 0xbf75fdf0
	v_fmaak_f32 v208, v206, v208, 0xbf75fdf0
	v_fmaak_f32 v214, v212, v214, 0xbf75fdf0
	v_fmaak_f32 v220, v218, v220, 0xbf75fdf0
	v_min_f32_e32 v169, v169, v218
	v_fmaak_f32 v170, v168, v170, 0xbfb17218
	v_fmaak_f32 v208, v206, v208, 0xbfb17218
	v_fmaak_f32 v214, v212, v214, 0xbfb17218
	v_fmaak_f32 v220, v218, v220, 0xbfb17218
	v_cmp_nlt_f32_e32 vcc, 0xbe38aa3b, v169
	v_mul_f32_e32 v170, v170, v168
	v_mul_f32_e32 v208, v208, v206
	v_mul_f32_e32 v214, v214, v212
	v_mul_f32_e32 v220, v220, v218
	s_cbranch_vccnz .Lscan1_far1
.Lscan1_back1:
	v_sqrt_f32_e32 v170, v170
	v_sqrt_f32_e32 v208, v208
	v_sqrt_f32_e32 v214, v214
	v_sqrt_f32_e32 v220, v220
	v_mul_f32_e32 v167, v167, v170
	v_mul_f32_e32 v205, v205, v208
	v_mul_f32_e32 v211, v211, v214
	v_mul_f32_e32 v217, v217, v220
	ds_read_b128 v[150:153], v230 offset:128
	ds_read_b128 v[154:157], v230 offset:512
	ds_read_b128 v[158:161], v230 offset:896
	ds_read_b128 v[162:165], v231 offset:128
	s_waitcnt lgkmcnt(0)
	v_mul_f32_e32 v24, v24, v222
	v_mul_f32_e32 v25, v25, v223
	v_mul_f32_e32 v26, v26, v224
	v_mul_f32_e32 v27, v27, v225
	v_mfma_f32_16x16x32_bf16 v[134:137], v[110:113], v[98:101], 0
	v_mfma_f32_16x16x32_bf16 v[138:141], v[122:125], v[98:101], 0
	v_mfma_f32_16x16x32_bf16 v[134:137], v[114:117], v[102:105], v[134:137]
	v_mfma_f32_16x16x32_bf16 v[138:141], v[126:129], v[102:105], v[138:141]
	v_mfma_f32_16x16x32_bf16 v[134:137], v[118:121], v[106:109], v[134:137]
	v_mfma_f32_16x16x32_bf16 v[138:141], v[130:133], v[106:109], v[138:141]
	v_fmac_f32_dpp v167, v167, v166 row_shr:1 row_mask:0xf bank_mask:0xf bound_ctrl:1
	v_fmac_f32_dpp v205, v205, v204 row_shr:1 row_mask:0xf bank_mask:0xf bound_ctrl:1
	v_fmac_f32_dpp v211, v211, v210 row_shr:1 row_mask:0xf bank_mask:0xf bound_ctrl:1
	v_fmac_f32_dpp v217, v217, v216 row_shr:1 row_mask:0xf bank_mask:0xf bound_ctrl:1
	v_mul_f32_dpp v166, v166, v166 row_shr:1 row_mask:0xf bank_mask:0xf
	v_mul_f32_dpp v204, v204, v204 row_shr:1 row_mask:0xf bank_mask:0xf
	v_mul_f32_dpp v210, v210, v210 row_shr:1 row_mask:0xf bank_mask:0xf
	v_mul_f32_dpp v216, v216, v216 row_shr:1 row_mask:0xf bank_mask:0xf
	v_fmac_f32_dpp v167, v167, v166 row_shr:2 row_mask:0xf bank_mask:0xf bound_ctrl:1
	v_fmac_f32_dpp v205, v205, v204 row_shr:2 row_mask:0xf bank_mask:0xf bound_ctrl:1
	v_fmac_f32_dpp v211, v211, v210 row_shr:2 row_mask:0xf bank_mask:0xf bound_ctrl:1
	v_fmac_f32_dpp v217, v217, v216 row_shr:2 row_mask:0xf bank_mask:0xf bound_ctrl:1
	v_mul_f32_dpp v166, v166, v166 row_shr:2 row_mask:0xf bank_mask:0xf
	v_mul_f32_dpp v204, v204, v204 row_shr:2 row_mask:0xf bank_mask:0xf
	v_mul_f32_dpp v210, v210, v210 row_shr:2 row_mask:0xf bank_mask:0xf
	v_mul_f32_dpp v216, v216, v216 row_shr:2 row_mask:0xf bank_mask:0xf
	v_fmac_f32_dpp v167, v167, v166 row_shr:4 row_mask:0xf bank_mask:0xf bound_ctrl:1
	v_fmac_f32_dpp v205, v205, v204 row_shr:4 row_mask:0xf bank_mask:0xf bound_ctrl:1
	v_fmac_f32_dpp v211, v211, v210 row_shr:4 row_mask:0xf bank_mask:0xf bound_ctrl:1
	v_fmac_f32_dpp v217, v217, v216 row_shr:4 row_mask:0xf bank_mask:0xf bound_ctrl:1
	v_mul_f32_dpp v166, v166, v166 row_shr:4 row_mask:0xf bank_mask:0xf
	v_mul_f32_dpp v204, v204, v204 row_shr:4 row_mask:0xf bank_mask:0xf
	v_mul_f32_dpp v210, v210, v210 row_shr:4 row_mask:0xf bank_mask:0xf
	v_mul_f32_dpp v216, v216, v216 row_shr:4 row_mask:0xf bank_mask:0xf
	v_fmac_f32_dpp v167, v167, v166 row_shr:8 row_mask:0xf bank_mask:0xf bound_ctrl:1
	v_fmac_f32_dpp v205, v205, v204 row_shr:8 row_mask:0xf bank_mask:0xf bound_ctrl:1
	v_fmac_f32_dpp v211, v211, v210 row_shr:8 row_mask:0xf bank_mask:0xf bound_ctrl:1
	v_fmac_f32_dpp v217, v217, v216 row_shr:8 row_mask:0xf bank_mask:0xf bound_ctrl:1
	v_mul_f32_dpp v166, v166, v166 row_shr:8 row_mask:0xf bank_mask:0xf
	v_mul_f32_dpp v204, v204, v204 row_shr:8 row_mask:0xf bank_mask:0xf
	v_mul_f32_dpp v210, v210, v210 row_shr:8 row_mask:0xf bank_mask:0xf
	v_mul_f32_dpp v216, v216, v216 row_shr:8 row_mask:0xf bank_mask:0xf
	v_fma_f32 v168, v166, v4, v167
	v_fma_f32 v206, v204, v5, v205
	v_fma_f32 v212, v210, v6, v211
	v_fma_f32 v218, v216, v7, v217
	ds_bpermute_b32 v4, v232, v168
	ds_bpermute_b32 v5, v232, v206
	ds_bpermute_b32 v6, v232, v212
	ds_bpermute_b32 v7, v232, v218
	ds_bpermute_b32 v222, v232, v166
	ds_bpermute_b32 v223, v232, v204
	ds_bpermute_b32 v224, v232, v210
	ds_bpermute_b32 v225, v232, v216
	ds_read_b128 v[110:113], v229 offset:9984
	ds_read_b128 v[122:125], v229 offset:29952
	ds_read_b128 v[114:117], v229 offset:10048
	ds_read_b128 v[126:129], v229 offset:30016
	ds_read_b128 v[118:121], v229 offset:10112
	ds_read_b128 v[130:133], v229 offset:30080
	v_fmamk_f32 v166, v134, 0xbfb8aa3b, v150
	v_fmamk_f32 v204, v135, 0xbfb8aa3b, v151
	v_fmamk_f32 v210, v136, 0xbfb8aa3b, v152
	v_fmamk_f32 v216, v137, 0xbfb8aa3b, v153
	v_fmamk_f32 v167, v138, 0xbfb8aa3b, v154
	v_fmamk_f32 v205, v139, 0xbfb8aa3b, v155
	v_fmamk_f32 v211, v140, 0xbfb8aa3b, v156
	v_fmamk_f32 v217, v141, 0xbfb8aa3b, v157
	v_exp_f32_e32 v166, v166
	v_exp_f32_e32 v204, v204
	v_exp_f32_e32 v210, v210
	v_exp_f32_e32 v216, v216
	v_exp_f32_e32 v167, v167
	v_exp_f32_e32 v205, v205
	v_exp_f32_e32 v211, v211
	v_exp_f32_e32 v217, v217
	v_add_f32_e32 v166, 1.0, v166
	v_add_f32_e32 v204, 1.0, v204
	v_add_f32_e32 v210, 1.0, v210
	v_add_f32_e32 v216, 1.0, v216
	v_add_f32_e32 v167, 1.0, v167
	v_add_f32_e32 v205, 1.0, v205
	v_add_f32_e32 v211, 1.0, v211
	v_add_f32_e32 v217, 1.0, v217
	v_rcp_f32_e32 v166, v166
	v_rcp_f32_e32 v204, v204
	v_rcp_f32_e32 v210, v210
	v_rcp_f32_e32 v216, v216
	v_rcp_f32_e32 v167, v167
	v_rcp_f32_e32 v205, v205
	v_rcp_f32_e32 v211, v211
	v_rcp_f32_e32 v217, v217
	v_mul_f32_e32 v168, v158, v166
	v_mul_f32_e32 v206, v159, v204
	v_mul_f32_e32 v212, v160, v210
	v_mul_f32_e32 v218, v161, v216
	v_mul_f32_e32 v167, v162, v167
	v_mul_f32_e32 v205, v163, v205
	v_mul_f32_e32 v211, v164, v211
	v_mul_f32_e32 v217, v165, v217
	v_exp_f32_e32 v166, v168
	v_exp_f32_e32 v204, v206
	v_exp_f32_e32 v210, v212
	v_exp_f32_e32 v216, v218
	v_fmaak_f32 v170, v168, v248, 0xbe1d955b
	v_fmaak_f32 v208, v206, v248, 0xbe1d955b
	v_fmaak_f32 v214, v212, v248, 0xbe1d955b
	v_fmaak_f32 v220, v218, v248, 0xbe1d955b
	v_fmaak_f32 v170, v168, v170, 0xbee35847
	v_fmaak_f32 v208, v206, v208, 0xbee35847
	v_fmaak_f32 v214, v212, v214, 0xbee35847
	v_fmaak_f32 v220, v218, v220, 0xbee35847
	v_min3_f32 v169, v168, v206, v212
	v_fmaak_f32 v170, v168, v170, 0xbf75fdf0
	v_fmaak_f32 v208, v206, v208, 0xbf75fdf0
	v_fmaak_f32 v214, v212, v214, 0xbf75fdf0
	v_fmaak_f32 v220, v218, v220, 0xbf75fdf0
	v_min_f32_e32 v169, v169, v218
	v_fmaak_f32 v170, v168, v170, 0xbfb17218
	v_fmaak_f32 v208, v206, v208, 0xbfb17218
	v_fmaak_f32 v214, v212, v214, 0xbfb17218
	v_fmaak_f32 v220, v218, v220, 0xbfb17218
	v_cmp_nlt_f32_e32 vcc, 0xbe38aa3b, v169
	v_mul_f32_e32 v170, v170, v168
	v_mul_f32_e32 v208, v208, v206
	v_mul_f32_e32 v214, v214, v212
	v_mul_f32_e32 v220, v220, v218
	s_cbranch_vccnz .Lscan1_far2
.Lscan1_back2:
	v_sqrt_f32_e32 v170, v170
	v_sqrt_f32_e32 v208, v208
	v_sqrt_f32_e32 v214, v214
	v_sqrt_f32_e32 v220, v220
	v_mul_f32_e32 v167, v167, v170
	v_mul_f32_e32 v205, v205, v208
	v_mul_f32_e32 v211, v211, v214
	v_mul_f32_e32 v217, v217, v220
	ds_read_b128 v[150:153], v230 offset:192
	ds_read_b128 v[154:157], v230 offset:576
	ds_read_b128 v[158:161], v230 offset:960
	ds_read_b128 v[162:165], v231 offset:192
	s_waitcnt lgkmcnt(0)
	v_mul_f32_e32 v28, v28, v222
	v_mul_f32_e32 v29, v29, v223
	v_mul_f32_e32 v30, v30, v224
	v_mul_f32_e32 v31, v31, v225
	v_mfma_f32_16x16x32_bf16 v[142:145], v[110:113], v[98:101], 0
	v_mfma_f32_16x16x32_bf16 v[146:149], v[122:125], v[98:101], 0
	v_mfma_f32_16x16x32_bf16 v[142:145], v[114:117], v[102:105], v[142:145]
	v_mfma_f32_16x16x32_bf16 v[146:149], v[126:129], v[102:105], v[146:149]
	v_mfma_f32_16x16x32_bf16 v[142:145], v[118:121], v[106:109], v[142:145]
	v_mfma_f32_16x16x32_bf16 v[146:149], v[130:133], v[106:109], v[146:149]
	v_fmac_f32_dpp v167, v167, v166 row_shr:1 row_mask:0xf bank_mask:0xf bound_ctrl:1
	v_fmac_f32_dpp v205, v205, v204 row_shr:1 row_mask:0xf bank_mask:0xf bound_ctrl:1
	v_fmac_f32_dpp v211, v211, v210 row_shr:1 row_mask:0xf bank_mask:0xf bound_ctrl:1
	v_fmac_f32_dpp v217, v217, v216 row_shr:1 row_mask:0xf bank_mask:0xf bound_ctrl:1
	v_mul_f32_dpp v166, v166, v166 row_shr:1 row_mask:0xf bank_mask:0xf
	v_mul_f32_dpp v204, v204, v204 row_shr:1 row_mask:0xf bank_mask:0xf
	v_mul_f32_dpp v210, v210, v210 row_shr:1 row_mask:0xf bank_mask:0xf
	v_mul_f32_dpp v216, v216, v216 row_shr:1 row_mask:0xf bank_mask:0xf
	v_fmac_f32_dpp v167, v167, v166 row_shr:2 row_mask:0xf bank_mask:0xf bound_ctrl:1
	v_fmac_f32_dpp v205, v205, v204 row_shr:2 row_mask:0xf bank_mask:0xf bound_ctrl:1
	v_fmac_f32_dpp v211, v211, v210 row_shr:2 row_mask:0xf bank_mask:0xf bound_ctrl:1
	v_fmac_f32_dpp v217, v217, v216 row_shr:2 row_mask:0xf bank_mask:0xf bound_ctrl:1
	v_mul_f32_dpp v166, v166, v166 row_shr:2 row_mask:0xf bank_mask:0xf
	v_mul_f32_dpp v204, v204, v204 row_shr:2 row_mask:0xf bank_mask:0xf
	v_mul_f32_dpp v210, v210, v210 row_shr:2 row_mask:0xf bank_mask:0xf
	v_mul_f32_dpp v216, v216, v216 row_shr:2 row_mask:0xf bank_mask:0xf
	v_fmac_f32_dpp v167, v167, v166 row_shr:4 row_mask:0xf bank_mask:0xf bound_ctrl:1
	v_fmac_f32_dpp v205, v205, v204 row_shr:4 row_mask:0xf bank_mask:0xf bound_ctrl:1
	v_fmac_f32_dpp v211, v211, v210 row_shr:4 row_mask:0xf bank_mask:0xf bound_ctrl:1
	v_fmac_f32_dpp v217, v217, v216 row_shr:4 row_mask:0xf bank_mask:0xf bound_ctrl:1
	v_mul_f32_dpp v166, v166, v166 row_shr:4 row_mask:0xf bank_mask:0xf
	v_mul_f32_dpp v204, v204, v204 row_shr:4 row_mask:0xf bank_mask:0xf
	v_mul_f32_dpp v210, v210, v210 row_shr:4 row_mask:0xf bank_mask:0xf
	v_mul_f32_dpp v216, v216, v216 row_shr:4 row_mask:0xf bank_mask:0xf
	v_fmac_f32_dpp v167, v167, v166 row_shr:8 row_mask:0xf bank_mask:0xf bound_ctrl:1
	v_fmac_f32_dpp v205, v205, v204 row_shr:8 row_mask:0xf bank_mask:0xf bound_ctrl:1
	v_fmac_f32_dpp v211, v211, v210 row_shr:8 row_mask:0xf bank_mask:0xf bound_ctrl:1
	v_fmac_f32_dpp v217, v217, v216 row_shr:8 row_mask:0xf bank_mask:0xf bound_ctrl:1
	v_mul_f32_dpp v166, v166, v166 row_shr:8 row_mask:0xf bank_mask:0xf
	v_mul_f32_dpp v204, v204, v204 row_shr:8 row_mask:0xf bank_mask:0xf
	v_mul_f32_dpp v210, v210, v210 row_shr:8 row_mask:0xf bank_mask:0xf
	v_mul_f32_dpp v216, v216, v216 row_shr:8 row_mask:0xf bank_mask:0xf
	v_fma_f32 v168, v166, v8, v167
	v_fma_f32 v206, v204, v9, v205
	v_fma_f32 v212, v210, v10, v211
	v_fma_f32 v218, v216, v11, v217
	ds_bpermute_b32 v8, v232, v168
	ds_bpermute_b32 v9, v232, v206
	ds_bpermute_b32 v10, v232, v212
	ds_bpermute_b32 v11, v232, v218
	ds_bpermute_b32 v222, v232, v166
	ds_bpermute_b32 v223, v232, v204
	ds_bpermute_b32 v224, v232, v210
	ds_bpermute_b32 v225, v232, v216
	ds_read_b128 v[110:113], v229 offset:13312
	ds_read_b128 v[122:125], v229 offset:33280
	ds_read_b128 v[114:117], v229 offset:13376
	ds_read_b128 v[126:129], v229 offset:33344
	ds_read_b128 v[118:121], v229 offset:13440
	ds_read_b128 v[130:133], v229 offset:33408
	v_fmamk_f32 v166, v142, 0xbfb8aa3b, v150
	v_fmamk_f32 v204, v143, 0xbfb8aa3b, v151
	v_fmamk_f32 v210, v144, 0xbfb8aa3b, v152
	v_fmamk_f32 v216, v145, 0xbfb8aa3b, v153
	v_fmamk_f32 v167, v146, 0xbfb8aa3b, v154
	v_fmamk_f32 v205, v147, 0xbfb8aa3b, v155
	v_fmamk_f32 v211, v148, 0xbfb8aa3b, v156
	v_fmamk_f32 v217, v149, 0xbfb8aa3b, v157
	v_exp_f32_e32 v166, v166
	v_exp_f32_e32 v204, v204
	v_exp_f32_e32 v210, v210
	v_exp_f32_e32 v216, v216
	v_exp_f32_e32 v167, v167
	v_exp_f32_e32 v205, v205
	v_exp_f32_e32 v211, v211
	v_exp_f32_e32 v217, v217
	v_add_f32_e32 v166, 1.0, v166
	v_add_f32_e32 v204, 1.0, v204
	v_add_f32_e32 v210, 1.0, v210
	v_add_f32_e32 v216, 1.0, v216
	v_add_f32_e32 v167, 1.0, v167
	v_add_f32_e32 v205, 1.0, v205
	v_add_f32_e32 v211, 1.0, v211
	v_add_f32_e32 v217, 1.0, v217
	v_rcp_f32_e32 v166, v166
	v_rcp_f32_e32 v204, v204
	v_rcp_f32_e32 v210, v210
	v_rcp_f32_e32 v216, v216
	v_rcp_f32_e32 v167, v167
	v_rcp_f32_e32 v205, v205
	v_rcp_f32_e32 v211, v211
	v_rcp_f32_e32 v217, v217
	v_mul_f32_e32 v168, v158, v166
	v_mul_f32_e32 v206, v159, v204
	v_mul_f32_e32 v212, v160, v210
	v_mul_f32_e32 v218, v161, v216
	v_mul_f32_e32 v167, v162, v167
	v_mul_f32_e32 v205, v163, v205
	v_mul_f32_e32 v211, v164, v211
	v_mul_f32_e32 v217, v165, v217
	v_exp_f32_e32 v166, v168
	v_exp_f32_e32 v204, v206
	v_exp_f32_e32 v210, v212
	v_exp_f32_e32 v216, v218
	v_fmaak_f32 v170, v168, v248, 0xbe1d955b
	v_fmaak_f32 v208, v206, v248, 0xbe1d955b
	v_fmaak_f32 v214, v212, v248, 0xbe1d955b
	v_fmaak_f32 v220, v218, v248, 0xbe1d955b
	v_fmaak_f32 v170, v168, v170, 0xbee35847
	v_fmaak_f32 v208, v206, v208, 0xbee35847
	v_fmaak_f32 v214, v212, v214, 0xbee35847
	v_fmaak_f32 v220, v218, v220, 0xbee35847
	v_min3_f32 v169, v168, v206, v212
	v_fmaak_f32 v170, v168, v170, 0xbf75fdf0
	v_fmaak_f32 v208, v206, v208, 0xbf75fdf0
	v_fmaak_f32 v214, v212, v214, 0xbf75fdf0
	v_fmaak_f32 v220, v218, v220, 0xbf75fdf0
	v_min_f32_e32 v169, v169, v218
	v_fmaak_f32 v170, v168, v170, 0xbfb17218
	v_fmaak_f32 v208, v206, v208, 0xbfb17218
	v_fmaak_f32 v214, v212, v214, 0xbfb17218
	v_fmaak_f32 v220, v218, v220, 0xbfb17218
	v_cmp_nlt_f32_e32 vcc, 0xbe38aa3b, v169
	v_mul_f32_e32 v170, v170, v168
	v_mul_f32_e32 v208, v208, v206
	v_mul_f32_e32 v214, v214, v212
	v_mul_f32_e32 v220, v220, v218
	s_cbranch_vccnz .Lscan1_far3
.Lscan1_back3:
	v_sqrt_f32_e32 v170, v170
	v_sqrt_f32_e32 v208, v208
	v_sqrt_f32_e32 v214, v214
	v_sqrt_f32_e32 v220, v220
	v_mul_f32_e32 v167, v167, v170
	v_mul_f32_e32 v205, v205, v208
	v_mul_f32_e32 v211, v211, v214
	v_mul_f32_e32 v217, v217, v220
	ds_read_b128 v[150:153], v230 offset:256
	ds_read_b128 v[154:157], v230 offset:640
	ds_read_b128 v[158:161], v230 offset:1024
	ds_read_b128 v[162:165], v231 offset:256
	s_waitcnt lgkmcnt(0)
	v_mul_f32_e32 v32, v32, v222
	v_mul_f32_e32 v33, v33, v223
	v_mul_f32_e32 v34, v34, v224
	v_mul_f32_e32 v35, v35, v225
	v_mfma_f32_16x16x32_bf16 v[134:137], v[110:113], v[98:101], 0
	v_mfma_f32_16x16x32_bf16 v[138:141], v[122:125], v[98:101], 0
	v_mfma_f32_16x16x32_bf16 v[134:137], v[114:117], v[102:105], v[134:137]
	v_mfma_f32_16x16x32_bf16 v[138:141], v[126:129], v[102:105], v[138:141]
	v_mfma_f32_16x16x32_bf16 v[134:137], v[118:121], v[106:109], v[134:137]
	v_mfma_f32_16x16x32_bf16 v[138:141], v[130:133], v[106:109], v[138:141]
	v_fmac_f32_dpp v167, v167, v166 row_shr:1 row_mask:0xf bank_mask:0xf bound_ctrl:1
	v_fmac_f32_dpp v205, v205, v204 row_shr:1 row_mask:0xf bank_mask:0xf bound_ctrl:1
	v_fmac_f32_dpp v211, v211, v210 row_shr:1 row_mask:0xf bank_mask:0xf bound_ctrl:1
	v_fmac_f32_dpp v217, v217, v216 row_shr:1 row_mask:0xf bank_mask:0xf bound_ctrl:1
	v_mul_f32_dpp v166, v166, v166 row_shr:1 row_mask:0xf bank_mask:0xf
	v_mul_f32_dpp v204, v204, v204 row_shr:1 row_mask:0xf bank_mask:0xf
	v_mul_f32_dpp v210, v210, v210 row_shr:1 row_mask:0xf bank_mask:0xf
	v_mul_f32_dpp v216, v216, v216 row_shr:1 row_mask:0xf bank_mask:0xf
	v_fmac_f32_dpp v167, v167, v166 row_shr:2 row_mask:0xf bank_mask:0xf bound_ctrl:1
	v_fmac_f32_dpp v205, v205, v204 row_shr:2 row_mask:0xf bank_mask:0xf bound_ctrl:1
	v_fmac_f32_dpp v211, v211, v210 row_shr:2 row_mask:0xf bank_mask:0xf bound_ctrl:1
	v_fmac_f32_dpp v217, v217, v216 row_shr:2 row_mask:0xf bank_mask:0xf bound_ctrl:1
	v_mul_f32_dpp v166, v166, v166 row_shr:2 row_mask:0xf bank_mask:0xf
	v_mul_f32_dpp v204, v204, v204 row_shr:2 row_mask:0xf bank_mask:0xf
	v_mul_f32_dpp v210, v210, v210 row_shr:2 row_mask:0xf bank_mask:0xf
	v_mul_f32_dpp v216, v216, v216 row_shr:2 row_mask:0xf bank_mask:0xf
	v_fmac_f32_dpp v167, v167, v166 row_shr:4 row_mask:0xf bank_mask:0xf bound_ctrl:1
	v_fmac_f32_dpp v205, v205, v204 row_shr:4 row_mask:0xf bank_mask:0xf bound_ctrl:1
	v_fmac_f32_dpp v211, v211, v210 row_shr:4 row_mask:0xf bank_mask:0xf bound_ctrl:1
	v_fmac_f32_dpp v217, v217, v216 row_shr:4 row_mask:0xf bank_mask:0xf bound_ctrl:1
	v_mul_f32_dpp v166, v166, v166 row_shr:4 row_mask:0xf bank_mask:0xf
	v_mul_f32_dpp v204, v204, v204 row_shr:4 row_mask:0xf bank_mask:0xf
	v_mul_f32_dpp v210, v210, v210 row_shr:4 row_mask:0xf bank_mask:0xf
	v_mul_f32_dpp v216, v216, v216 row_shr:4 row_mask:0xf bank_mask:0xf
	v_fmac_f32_dpp v167, v167, v166 row_shr:8 row_mask:0xf bank_mask:0xf bound_ctrl:1
	v_fmac_f32_dpp v205, v205, v204 row_shr:8 row_mask:0xf bank_mask:0xf bound_ctrl:1
	v_fmac_f32_dpp v211, v211, v210 row_shr:8 row_mask:0xf bank_mask:0xf bound_ctrl:1
	v_fmac_f32_dpp v217, v217, v216 row_shr:8 row_mask:0xf bank_mask:0xf bound_ctrl:1
	v_mul_f32_dpp v166, v166, v166 row_shr:8 row_mask:0xf bank_mask:0xf
	v_mul_f32_dpp v204, v204, v204 row_shr:8 row_mask:0xf bank_mask:0xf
	v_mul_f32_dpp v210, v210, v210 row_shr:8 row_mask:0xf bank_mask:0xf
	v_mul_f32_dpp v216, v216, v216 row_shr:8 row_mask:0xf bank_mask:0xf
	v_fma_f32 v168, v166, v12, v167
	v_fma_f32 v206, v204, v13, v205
	v_fma_f32 v212, v210, v14, v211
	v_fma_f32 v218, v216, v15, v217
	ds_bpermute_b32 v12, v232, v168
	ds_bpermute_b32 v13, v232, v206
	ds_bpermute_b32 v14, v232, v212
	ds_bpermute_b32 v15, v232, v218
	ds_bpermute_b32 v222, v232, v166
	ds_bpermute_b32 v223, v232, v204
	ds_bpermute_b32 v224, v232, v210
	ds_bpermute_b32 v225, v232, v216
	ds_read_b128 v[110:113], v229 offset:16640
	ds_read_b128 v[122:125], v229 offset:36608
	ds_read_b128 v[114:117], v229 offset:16704
	ds_read_b128 v[126:129], v229 offset:36672
	ds_read_b128 v[118:121], v229 offset:16768
	ds_read_b128 v[130:133], v229 offset:36736
	v_fmamk_f32 v166, v134, 0xbfb8aa3b, v150
	v_fmamk_f32 v204, v135, 0xbfb8aa3b, v151
	v_fmamk_f32 v210, v136, 0xbfb8aa3b, v152
	v_fmamk_f32 v216, v137, 0xbfb8aa3b, v153
	v_fmamk_f32 v167, v138, 0xbfb8aa3b, v154
	v_fmamk_f32 v205, v139, 0xbfb8aa3b, v155
	v_fmamk_f32 v211, v140, 0xbfb8aa3b, v156
	v_fmamk_f32 v217, v141, 0xbfb8aa3b, v157
	v_exp_f32_e32 v166, v166
	v_exp_f32_e32 v204, v204
	v_exp_f32_e32 v210, v210
	v_exp_f32_e32 v216, v216
	v_exp_f32_e32 v167, v167
	v_exp_f32_e32 v205, v205
	v_exp_f32_e32 v211, v211
	v_exp_f32_e32 v217, v217
	v_add_f32_e32 v166, 1.0, v166
	v_add_f32_e32 v204, 1.0, v204
	v_add_f32_e32 v210, 1.0, v210
	v_add_f32_e32 v216, 1.0, v216
	v_add_f32_e32 v167, 1.0, v167
	v_add_f32_e32 v205, 1.0, v205
	v_add_f32_e32 v211, 1.0, v211
	v_add_f32_e32 v217, 1.0, v217
	v_rcp_f32_e32 v166, v166
	v_rcp_f32_e32 v204, v204
	v_rcp_f32_e32 v210, v210
	v_rcp_f32_e32 v216, v216
	v_rcp_f32_e32 v167, v167
	v_rcp_f32_e32 v205, v205
	v_rcp_f32_e32 v211, v211
	v_rcp_f32_e32 v217, v217
	v_mul_f32_e32 v168, v158, v166
	v_mul_f32_e32 v206, v159, v204
	v_mul_f32_e32 v212, v160, v210
	v_mul_f32_e32 v218, v161, v216
	v_mul_f32_e32 v167, v162, v167
	v_mul_f32_e32 v205, v163, v205
	v_mul_f32_e32 v211, v164, v211
	v_mul_f32_e32 v217, v165, v217
	v_exp_f32_e32 v166, v168
	v_exp_f32_e32 v204, v206
	v_exp_f32_e32 v210, v212
	v_exp_f32_e32 v216, v218
	v_fmaak_f32 v170, v168, v248, 0xbe1d955b
	v_fmaak_f32 v208, v206, v248, 0xbe1d955b
	v_fmaak_f32 v214, v212, v248, 0xbe1d955b
	v_fmaak_f32 v220, v218, v248, 0xbe1d955b
	v_fmaak_f32 v170, v168, v170, 0xbee35847
	v_fmaak_f32 v208, v206, v208, 0xbee35847
	v_fmaak_f32 v214, v212, v214, 0xbee35847
	v_fmaak_f32 v220, v218, v220, 0xbee35847
	v_min3_f32 v169, v168, v206, v212
	v_fmaak_f32 v170, v168, v170, 0xbf75fdf0
	v_fmaak_f32 v208, v206, v208, 0xbf75fdf0
	v_fmaak_f32 v214, v212, v214, 0xbf75fdf0
	v_fmaak_f32 v220, v218, v220, 0xbf75fdf0
	v_min_f32_e32 v169, v169, v218
	v_fmaak_f32 v170, v168, v170, 0xbfb17218
	v_fmaak_f32 v208, v206, v208, 0xbfb17218
	v_fmaak_f32 v214, v212, v214, 0xbfb17218
	v_fmaak_f32 v220, v218, v220, 0xbfb17218
	v_cmp_nlt_f32_e32 vcc, 0xbe38aa3b, v169
	v_mul_f32_e32 v170, v170, v168
	v_mul_f32_e32 v208, v208, v206
	v_mul_f32_e32 v214, v214, v212
	v_mul_f32_e32 v220, v220, v218
	s_cbranch_vccnz .Lscan1_far4
.Lscan1_back4:
	v_sqrt_f32_e32 v170, v170
	v_sqrt_f32_e32 v208, v208
	v_sqrt_f32_e32 v214, v214
	v_sqrt_f32_e32 v220, v220
	v_mul_f32_e32 v167, v167, v170
	v_mul_f32_e32 v205, v205, v208
	v_mul_f32_e32 v211, v211, v214
	v_mul_f32_e32 v217, v217, v220
	ds_read_b128 v[150:153], v230 offset:320
	ds_read_b128 v[154:157], v230 offset:704
	ds_read_b128 v[158:161], v230 offset:1088
	ds_read_b128 v[162:165], v231 offset:320
	s_waitcnt lgkmcnt(0)
	v_mul_f32_e32 v36, v36, v222
	v_mul_f32_e32 v37, v37, v223
	v_mul_f32_e32 v38, v38, v224
	v_mul_f32_e32 v39, v39, v225
	v_mfma_f32_16x16x32_bf16 v[142:145], v[110:113], v[98:101], 0
	v_mfma_f32_16x16x32_bf16 v[146:149], v[122:125], v[98:101], 0
	v_mfma_f32_16x16x32_bf16 v[142:145], v[114:117], v[102:105], v[142:145]
	v_mfma_f32_16x16x32_bf16 v[146:149], v[126:129], v[102:105], v[146:149]
	v_mfma_f32_16x16x32_bf16 v[142:145], v[118:121], v[106:109], v[142:145]
	v_mfma_f32_16x16x32_bf16 v[146:149], v[130:133], v[106:109], v[146:149]
	v_fmac_f32_dpp v167, v167, v166 row_shr:1 row_mask:0xf bank_mask:0xf bound_ctrl:1
	v_fmac_f32_dpp v205, v205, v204 row_shr:1 row_mask:0xf bank_mask:0xf bound_ctrl:1
	v_fmac_f32_dpp v211, v211, v210 row_shr:1 row_mask:0xf bank_mask:0xf bound_ctrl:1
	v_fmac_f32_dpp v217, v217, v216 row_shr:1 row_mask:0xf bank_mask:0xf bound_ctrl:1
	v_mul_f32_dpp v166, v166, v166 row_shr:1 row_mask:0xf bank_mask:0xf
	v_mul_f32_dpp v204, v204, v204 row_shr:1 row_mask:0xf bank_mask:0xf
	v_mul_f32_dpp v210, v210, v210 row_shr:1 row_mask:0xf bank_mask:0xf
	v_mul_f32_dpp v216, v216, v216 row_shr:1 row_mask:0xf bank_mask:0xf
	v_fmac_f32_dpp v167, v167, v166 row_shr:2 row_mask:0xf bank_mask:0xf bound_ctrl:1
	v_fmac_f32_dpp v205, v205, v204 row_shr:2 row_mask:0xf bank_mask:0xf bound_ctrl:1
	v_fmac_f32_dpp v211, v211, v210 row_shr:2 row_mask:0xf bank_mask:0xf bound_ctrl:1
	v_fmac_f32_dpp v217, v217, v216 row_shr:2 row_mask:0xf bank_mask:0xf bound_ctrl:1
	v_mul_f32_dpp v166, v166, v166 row_shr:2 row_mask:0xf bank_mask:0xf
	v_mul_f32_dpp v204, v204, v204 row_shr:2 row_mask:0xf bank_mask:0xf
	v_mul_f32_dpp v210, v210, v210 row_shr:2 row_mask:0xf bank_mask:0xf
	v_mul_f32_dpp v216, v216, v216 row_shr:2 row_mask:0xf bank_mask:0xf
	v_fmac_f32_dpp v167, v167, v166 row_shr:4 row_mask:0xf bank_mask:0xf bound_ctrl:1
	v_fmac_f32_dpp v205, v205, v204 row_shr:4 row_mask:0xf bank_mask:0xf bound_ctrl:1
	v_fmac_f32_dpp v211, v211, v210 row_shr:4 row_mask:0xf bank_mask:0xf bound_ctrl:1
	v_fmac_f32_dpp v217, v217, v216 row_shr:4 row_mask:0xf bank_mask:0xf bound_ctrl:1
	v_mul_f32_dpp v166, v166, v166 row_shr:4 row_mask:0xf bank_mask:0xf
	v_mul_f32_dpp v204, v204, v204 row_shr:4 row_mask:0xf bank_mask:0xf
	v_mul_f32_dpp v210, v210, v210 row_shr:4 row_mask:0xf bank_mask:0xf
	v_mul_f32_dpp v216, v216, v216 row_shr:4 row_mask:0xf bank_mask:0xf
	v_fmac_f32_dpp v167, v167, v166 row_shr:8 row_mask:0xf bank_mask:0xf bound_ctrl:1
	v_fmac_f32_dpp v205, v205, v204 row_shr:8 row_mask:0xf bank_mask:0xf bound_ctrl:1
	v_fmac_f32_dpp v211, v211, v210 row_shr:8 row_mask:0xf bank_mask:0xf bound_ctrl:1
	v_fmac_f32_dpp v217, v217, v216 row_shr:8 row_mask:0xf bank_mask:0xf bound_ctrl:1
	v_mul_f32_dpp v166, v166, v166 row_shr:8 row_mask:0xf bank_mask:0xf
	v_mul_f32_dpp v204, v204, v204 row_shr:8 row_mask:0xf bank_mask:0xf
	v_mul_f32_dpp v210, v210, v210 row_shr:8 row_mask:0xf bank_mask:0xf
	v_mul_f32_dpp v216, v216, v216 row_shr:8 row_mask:0xf bank_mask:0xf
	v_fma_f32 v168, v166, v16, v167
	v_fma_f32 v206, v204, v17, v205
	v_fma_f32 v212, v210, v18, v211
	v_fma_f32 v218, v216, v19, v217
	ds_bpermute_b32 v16, v232, v168
	ds_bpermute_b32 v17, v232, v206
	ds_bpermute_b32 v18, v232, v212
	ds_bpermute_b32 v19, v232, v218
	ds_bpermute_b32 v222, v232, v166
	ds_bpermute_b32 v223, v232, v204
	ds_bpermute_b32 v224, v232, v210
	ds_bpermute_b32 v225, v232, v216
	v_fmamk_f32 v166, v142, 0xbfb8aa3b, v150
	v_fmamk_f32 v204, v143, 0xbfb8aa3b, v151
	v_fmamk_f32 v210, v144, 0xbfb8aa3b, v152
	v_fmamk_f32 v216, v145, 0xbfb8aa3b, v153
	v_fmamk_f32 v167, v146, 0xbfb8aa3b, v154
	v_fmamk_f32 v205, v147, 0xbfb8aa3b, v155
	v_fmamk_f32 v211, v148, 0xbfb8aa3b, v156
	v_fmamk_f32 v217, v149, 0xbfb8aa3b, v157
	v_exp_f32_e32 v166, v166
	v_exp_f32_e32 v204, v204
	v_exp_f32_e32 v210, v210
	v_exp_f32_e32 v216, v216
	v_exp_f32_e32 v167, v167
	v_exp_f32_e32 v205, v205
	v_exp_f32_e32 v211, v211
	v_exp_f32_e32 v217, v217
	v_add_f32_e32 v166, 1.0, v166
	v_add_f32_e32 v204, 1.0, v204
	v_add_f32_e32 v210, 1.0, v210
	v_add_f32_e32 v216, 1.0, v216
	v_add_f32_e32 v167, 1.0, v167
	v_add_f32_e32 v205, 1.0, v205
	v_add_f32_e32 v211, 1.0, v211
	v_add_f32_e32 v217, 1.0, v217
	v_rcp_f32_e32 v166, v166
	v_rcp_f32_e32 v204, v204
	v_rcp_f32_e32 v210, v210
	v_rcp_f32_e32 v216, v216
	v_rcp_f32_e32 v167, v167
	v_rcp_f32_e32 v205, v205
	v_rcp_f32_e32 v211, v211
	v_rcp_f32_e32 v217, v217
	v_mul_f32_e32 v168, v158, v166
	v_mul_f32_e32 v206, v159, v204
	v_mul_f32_e32 v212, v160, v210
	v_mul_f32_e32 v218, v161, v216
	v_mul_f32_e32 v167, v162, v167
	v_mul_f32_e32 v205, v163, v205
	v_mul_f32_e32 v211, v164, v211
	v_mul_f32_e32 v217, v165, v217
	v_exp_f32_e32 v166, v168
	v_exp_f32_e32 v204, v206
	v_exp_f32_e32 v210, v212
	v_exp_f32_e32 v216, v218
	v_fmaak_f32 v170, v168, v248, 0xbe1d955b
	v_fmaak_f32 v208, v206, v248, 0xbe1d955b
	v_fmaak_f32 v214, v212, v248, 0xbe1d955b
	v_fmaak_f32 v220, v218, v248, 0xbe1d955b
	v_fmaak_f32 v170, v168, v170, 0xbee35847
	v_fmaak_f32 v208, v206, v208, 0xbee35847
	v_fmaak_f32 v214, v212, v214, 0xbee35847
	v_fmaak_f32 v220, v218, v220, 0xbee35847
	v_min3_f32 v169, v168, v206, v212
	v_fmaak_f32 v170, v168, v170, 0xbf75fdf0
	v_fmaak_f32 v208, v206, v208, 0xbf75fdf0
	v_fmaak_f32 v214, v212, v214, 0xbf75fdf0
	v_fmaak_f32 v220, v218, v220, 0xbf75fdf0
	v_min_f32_e32 v169, v169, v218
	v_fmaak_f32 v170, v168, v170, 0xbfb17218
	v_fmaak_f32 v208, v206, v208, 0xbfb17218
	v_fmaak_f32 v214, v212, v214, 0xbfb17218
	v_fmaak_f32 v220, v218, v220, 0xbfb17218
	v_cmp_nlt_f32_e32 vcc, 0xbe38aa3b, v169
	v_mul_f32_e32 v170, v170, v168
	v_mul_f32_e32 v208, v208, v206
	v_mul_f32_e32 v214, v214, v212
	v_mul_f32_e32 v220, v220, v218
	s_cbranch_vccnz .Lscan1_far5
.Lscan1_back5:
	v_sqrt_f32_e32 v170, v170
	v_sqrt_f32_e32 v208, v208
	v_sqrt_f32_e32 v214, v214
	v_sqrt_f32_e32 v220, v220
	v_mul_f32_e32 v167, v167, v170
	v_mul_f32_e32 v205, v205, v208
	v_mul_f32_e32 v211, v211, v214
	v_mul_f32_e32 v217, v217, v220
	s_waitcnt lgkmcnt(0)
	v_mul_f32_e32 v40, v40, v222
	v_mul_f32_e32 v41, v41, v223
	v_mul_f32_e32 v42, v42, v224
	v_mul_f32_e32 v43, v43, v225
	v_fmac_f32_dpp v167, v167, v166 row_shr:1 row_mask:0xf bank_mask:0xf bound_ctrl:1
	v_fmac_f32_dpp v205, v205, v204 row_shr:1 row_mask:0xf bank_mask:0xf bound_ctrl:1
	v_fmac_f32_dpp v211, v211, v210 row_shr:1 row_mask:0xf bank_mask:0xf bound_ctrl:1
	v_fmac_f32_dpp v217, v217, v216 row_shr:1 row_mask:0xf bank_mask:0xf bound_ctrl:1
	v_mul_f32_dpp v166, v166, v166 row_shr:1 row_mask:0xf bank_mask:0xf
	v_mul_f32_dpp v204, v204, v204 row_shr:1 row_mask:0xf bank_mask:0xf
	v_mul_f32_dpp v210, v210, v210 row_shr:1 row_mask:0xf bank_mask:0xf
	v_mul_f32_dpp v216, v216, v216 row_shr:1 row_mask:0xf bank_mask:0xf
	v_fmac_f32_dpp v167, v167, v166 row_shr:2 row_mask:0xf bank_mask:0xf bound_ctrl:1
	v_fmac_f32_dpp v205, v205, v204 row_shr:2 row_mask:0xf bank_mask:0xf bound_ctrl:1
	v_fmac_f32_dpp v211, v211, v210 row_shr:2 row_mask:0xf bank_mask:0xf bound_ctrl:1
	v_fmac_f32_dpp v217, v217, v216 row_shr:2 row_mask:0xf bank_mask:0xf bound_ctrl:1
	v_mul_f32_dpp v166, v166, v166 row_shr:2 row_mask:0xf bank_mask:0xf
	v_mul_f32_dpp v204, v204, v204 row_shr:2 row_mask:0xf bank_mask:0xf
	v_mul_f32_dpp v210, v210, v210 row_shr:2 row_mask:0xf bank_mask:0xf
	v_mul_f32_dpp v216, v216, v216 row_shr:2 row_mask:0xf bank_mask:0xf
	v_fmac_f32_dpp v167, v167, v166 row_shr:4 row_mask:0xf bank_mask:0xf bound_ctrl:1
	v_fmac_f32_dpp v205, v205, v204 row_shr:4 row_mask:0xf bank_mask:0xf bound_ctrl:1
	v_fmac_f32_dpp v211, v211, v210 row_shr:4 row_mask:0xf bank_mask:0xf bound_ctrl:1
	v_fmac_f32_dpp v217, v217, v216 row_shr:4 row_mask:0xf bank_mask:0xf bound_ctrl:1
	v_mul_f32_dpp v166, v166, v166 row_shr:4 row_mask:0xf bank_mask:0xf
	v_mul_f32_dpp v204, v204, v204 row_shr:4 row_mask:0xf bank_mask:0xf
	v_mul_f32_dpp v210, v210, v210 row_shr:4 row_mask:0xf bank_mask:0xf
	v_mul_f32_dpp v216, v216, v216 row_shr:4 row_mask:0xf bank_mask:0xf
	v_fmac_f32_dpp v167, v167, v166 row_shr:8 row_mask:0xf bank_mask:0xf bound_ctrl:1
	v_fmac_f32_dpp v205, v205, v204 row_shr:8 row_mask:0xf bank_mask:0xf bound_ctrl:1
	v_fmac_f32_dpp v211, v211, v210 row_shr:8 row_mask:0xf bank_mask:0xf bound_ctrl:1
	v_fmac_f32_dpp v217, v217, v216 row_shr:8 row_mask:0xf bank_mask:0xf bound_ctrl:1
	v_mul_f32_dpp v166, v166, v166 row_shr:8 row_mask:0xf bank_mask:0xf
	v_mul_f32_dpp v204, v204, v204 row_shr:8 row_mask:0xf bank_mask:0xf
	v_mul_f32_dpp v210, v210, v210 row_shr:8 row_mask:0xf bank_mask:0xf
	v_mul_f32_dpp v216, v216, v216 row_shr:8 row_mask:0xf bank_mask:0xf
	v_fma_f32 v168, v166, v20, v167
	v_fma_f32 v206, v204, v21, v205
	v_fma_f32 v212, v210, v22, v211
	v_fma_f32 v218, v216, v23, v217
	ds_bpermute_b32 v20, v232, v168
	ds_bpermute_b32 v21, v232, v206
	ds_bpermute_b32 v22, v232, v212
	ds_bpermute_b32 v23, v232, v218
	ds_bpermute_b32 v222, v232, v166
	ds_bpermute_b32 v223, v232, v204
	ds_bpermute_b32 v224, v232, v210
	ds_bpermute_b32 v225, v232, v216
	s_waitcnt lgkmcnt(0)
	v_mul_f32_e32 v44, v44, v222
	v_mul_f32_e32 v45, v45, v223
	v_mul_f32_e32 v46, v46, v224
	v_mul_f32_e32 v47, v47, v225
	s_waitcnt vmcnt(0)
	v_mov_b32_e32 v66, v82
	v_mov_b32_e32 v67, v83
	v_mov_b32_e32 v68, v84
	v_mov_b32_e32 v69, v85
	v_mov_b32_e32 v70, v86
	v_mov_b32_e32 v71, v87
	v_mov_b32_e32 v72, v88
	v_mov_b32_e32 v73, v89
	v_mov_b32_e32 v74, v90
	v_mov_b32_e32 v75, v91
	v_mov_b32_e32 v76, v92
	v_mov_b32_e32 v77, v93
	v_mov_b32_e32 v78, v94
	v_mov_b32_e32 v79, v95
	v_mov_b32_e32 v80, v96
	v_mov_b32_e32 v81, v97
	s_add_i32 s64, s64, 1
	s_cmp_lt_u32 s64, 3
	s_cbranch_scc1 .Lscan1_sub
	s_mov_b32 s62, 0x10001
	s_mov_b32 s63, 0x10001
	s_mov_b64 exec, s[62:63]
	s_add_u32 s62, s6, 0x204000
	s_addc_u32 s63, s7, 0
	global_store_dwordx4 v237, v[24:27], s[6:7] offset:0
	global_store_dwordx4 v237, v[0:3], s[62:63] offset:0
	global_store_dwordx4 v237, v[28:31], s[6:7] offset:64
	global_store_dwordx4 v237, v[4:7], s[62:63] offset:64
	global_store_dwordx4 v237, v[32:35], s[6:7] offset:128
	global_store_dwordx4 v237, v[8:11], s[62:63] offset:128
	global_store_dwordx4 v237, v[36:39], s[6:7] offset:192
	global_store_dwordx4 v237, v[12:15], s[62:63] offset:192
	global_store_dwordx4 v237, v[40:43], s[6:7] offset:256
	global_store_dwordx4 v237, v[16:19], s[62:63] offset:256
	global_store_dwordx4 v237, v[44:47], s[6:7] offset:320
	global_store_dwordx4 v237, v[20:23], s[62:63] offset:320
	s_mov_b64 exec, -1
	s_add_i32 s23, s23, s42
.Lscan1_unit_test:
	s_cmpk_lt_u32 s23, 0x2b0
	s_cbranch_scc1 .Lscan1_unit
	s_waitcnt vmcnt(0) lgkmcnt(0)
	s_branch .Lscan1_end
.Lscan1_far0:
	v_cmp_nlt_f32_e32 vcc, 0xbe38aa3b, v168
	v_cmp_nlt_f32_e64 s[62:63], s55, v206
	v_cmp_nlt_f32_e64 s[56:57], s55, v212
	v_fma_f32 v171, -v166, v166, 1.0
	v_fma_f32 v209, -v204, v204, 1.0
	v_fma_f32 v215, -v210, v210, 1.0
	v_fma_f32 v221, -v216, v216, 1.0
	v_cndmask_b32_e32 v170, v170, v171, vcc
	v_cmp_nlt_f32_e32 vcc, 0xbe38aa3b, v218
	v_cndmask_b32_e64 v208, v208, v209, s[62:63]
	v_cndmask_b32_e64 v214, v214, v215, s[56:57]
	s_nop 0
	v_cndmask_b32_e32 v220, v220, v221, vcc
	s_branch .Lscan1_back0

.Lscan1_end:
.LBB0_366:
	v_readlane_b32 s6, v254, 4
	s_add_i32 s0, s87, 2
	v_readlane_b32 s7, v254, 5
	s_cmp_ge_i32 s0, s7
	s_cbranch_scc1 .LBB0_378
	s_cmp_lg_u32 s54, 0
	s_mov_b32 s20, s68
	s_cbranch_scc0 .LBB0_379
	v_mov_b32_e32 v0, v192
	s_add_i32 s12, s60, 1
	s_waitcnt vmcnt(0) lgkmcnt(0)
	s_barrier
	s_nop 0
	v_cmp_eq_u32_e32 vcc, 0, v0
	s_and_saveexec_b64 s[6:7], vcc
	s_cbranch_execz .LBB0_377
	s_mov_b64 s[10:11], exec
	v_mbcnt_lo_u32_b32 v0, s10, 0
	v_mbcnt_hi_u32_b32 v0, s11, v0
	v_cmp_eq_u32_e32 vcc, 0, v0
	buffer_wbl2 sc1
	s_and_saveexec_b64 s[8:9], vcc
	s_cbranch_execz .LBB0_371
	v_readlane_b32 s13, v254, 18
	s_lshl_b32 s13, s13, 2
	s_bcnt1_i32_b64 s10, s[10:11]
	v_mov_b32_e32 v1, s13
	v_mov_b32_e32 v2, s10
	global_atomic_add v1, v1, v2, s[18:19] offset:256 sc0

.Lscan2_staged:
	s_lshr_b32 s0, s23, 4
	s_lshl_b32 s0, s0, 3
	s_add_i32 s0, s0, s21
	s_mul_i32 s55, s0, 0x5f5
	s_lshr_b32 s55, s55, 16
	s_mul_i32 s56, s55, 43
	s_sub_i32 s56, s0, s56
	s_mul_i32 s57, s55, 0x810
	s_mul_i32 s39, s56, 48
	s_add_i32 s57, s57, s39
	s_mul_i32 s44, s57, 0x1800
	s_mul_hi_u32 s45, s57, 0x1800
	s_mul_i32 s39, s37, 0xc0
	s_add_i32 s39, s39, 0xc00
	s_add_u32 s44, s44, s39
	s_addc_u32 s45, s45, 0
	s_add_u32 s44, s44, s28
	s_addc_u32 s45, s45, s29
	s_add_u32 s62, s44, 0xffffb800
	s_addc_u32 s63, s45, -1
	global_load_dword v59, v233, s[62:63]
	s_add_u32 s62, s62, 0x1800
	s_addc_u32 s63, s63, 0
	global_load_dword v61, v233, s[62:63]
	s_add_u32 s62, s62, 0x1800
	s_addc_u32 s63, s63, 0
	global_load_dword v63, v233, s[62:63]
	s_mov_b64 s[62:63], s[44:45]
	global_load_dword v66, v233, s[62:63]
	s_add_u32 s62, s62, 0x1800
	s_addc_u32 s63, s63, 0
	global_load_dword v67, v233, s[62:63]
	s_add_u32 s62, s62, 0x1800
	s_addc_u32 s63, s63, 0
	global_load_dword v68, v233, s[62:63]
	s_add_u32 s62, s62, 0x1800
	s_addc_u32 s63, s63, 0
	global_load_dword v69, v233, s[62:63]
	s_add_u32 s62, s62, 0x1800
	s_addc_u32 s63, s63, 0
	global_load_dword v70, v233, s[62:63]
	s_add_u32 s62, s62, 0x1800
	s_addc_u32 s63, s63, 0
	global_load_dword v71, v233, s[62:63]
	s_add_u32 s62, s62, 0x1800
	s_addc_u32 s63, s63, 0
	global_load_dword v72, v233, s[62:63]
	s_add_u32 s62, s62, 0x1800
	s_addc_u32 s63, s63, 0
	global_load_dword v73, v233, s[62:63]
	s_add_u32 s62, s62, 0x1800
	s_addc_u32 s63, s63, 0
	global_load_dword v74, v233, s[62:63]
	s_add_u32 s62, s62, 0x1800
	s_addc_u32 s63, s63, 0
	global_load_dword v75, v233, s[62:63]
	s_add_u32 s62, s62, 0x1800
	s_addc_u32 s63, s63, 0
	global_load_dword v76, v233, s[62:63]
	s_add_u32 s62, s62, 0x1800
	s_addc_u32 s63, s63, 0
	global_load_dword v77, v233, s[62:63]
	s_add_u32 s62, s62, 0x1800
	s_addc_u32 s63, s63, 0
	global_load_dword v78, v233, s[62:63]
	s_add_u32 s62, s62, 0x1800
	s_addc_u32 s63, s63, 0
	global_load_dword v79, v233, s[62:63]
	s_add_u32 s62, s62, 0x1800
	s_addc_u32 s63, s63, 0
	global_load_dword v80, v233, s[62:63]
	s_add_u32 s62, s62, 0x1800
	s_addc_u32 s63, s63, 0
	global_load_dword v81, v233, s[62:63]
	s_add_u32 s62, s62, 0x1800
	s_addc_u32 s63, s63, 0
	s_mov_b64 s[44:45], s[62:63]
	s_mul_i32 s39, s37, 0x180
	s_add_u32 s62, s8, s39
	s_addc_u32 s63, s9, 0
	global_load_dwordx2 v[48:49], v234, s[62:63]
	s_add_u32 s62, s62, 0x1800
	s_addc_u32 s63, s63, 0
	global_load_dwordx2 v[50:51], v234, s[62:63]
	s_add_u32 s62, s62, 0x1800
	s_addc_u32 s63, s63, 0
	global_load_dwordx2 v[52:53], v234, s[62:63]
	s_add_u32 s62, s62, 0x1800
	s_addc_u32 s63, s63, 0
	global_load_dwordx2 v[54:55], v234, s[62:63]
	s_add_u32 s62, s10, s39
	s_addc_u32 s63, s11, 0
	global_load_dwordx2 v[56:57], v234, s[62:63]
	s_mul_i32 s39, s55, 43
	s_add_i32 s39, s39, s56
	s_mul_i32 s39, s39, 0x1800
	s_mul_i32 s0, s37, 0x180
	s_add_i32 s39, s39, s0
	s_add_u32 s62, s30, s39
	s_addc_u32 s63, s31, 0
	global_load_dwordx4 v[0:3], v237, s[62:63] offset:0
	global_load_dwordx4 v[4:7], v237, s[62:63] offset:64
	global_load_dwordx4 v[8:11], v237, s[62:63] offset:128
	global_load_dwordx4 v[12:15], v237, s[62:63] offset:192
	global_load_dwordx4 v[16:19], v237, s[62:63] offset:256
	global_load_dwordx4 v[20:23], v237, s[62:63] offset:320
	s_mul_i32 s6, s57, 0x1800
	s_mul_hi_u32 s7, s57, 0x1800
	s_mul_i32 s39, s37, 0xc0
	s_add_u32 s6, s6, s39
	s_addc_u32 s7, s7, 0
	s_add_u32 s6, s6, s28
	s_addc_u32 s7, s7, s29
	s_mul_i32 s100, s57, 0xc00
	s_mul_hi_u32 s101, s57, 0xc00
	s_add_u32 s100, s100, s39
	s_addc_u32 s101, s101, 0
	s_add_u32 s100, s100, s34
	s_addc_u32 s101, s101, s35
	v_mov_b32_e32 v248, 0xbd2ec3ff
	v_mov_b32_e32 v249, 0xbdd2d3e8
	s_waitcnt vmcnt(0)
	s_cmp_eq_u32 s56, 0
	s_cbranch_scc1 .Lscan2_hzero
	v_lshlrev_b32_e32 v58, 16, v59
	v_and_b32_e32 v59, 0xffff0000, v59
	v_lshlrev_b32_e32 v60, 16, v61
	v_and_b32_e32 v61, 0xffff0000, v61
	v_lshlrev_b32_e32 v62, 16, v63
	v_and_b32_e32 v63, 0xffff0000, v63
	s_branch .Lscan2_hdone

.Lscan2_sub:
	global_load_dwordx2 v[24:25], v235, s[6:7] offset:0
	global_load_dwordx2 v[26:27], v235, s[6:7] offset:32
	global_load_dwordx2 v[28:29], v235, s[6:7] offset:64
	global_load_dwordx2 v[30:31], v235, s[6:7] offset:96
	global_load_dwordx2 v[32:33], v235, s[6:7] offset:128
	global_load_dwordx2 v[34:35], v235, s[6:7] offset:160
	s_mov_b64 s[62:63], s[44:45]
	global_load_dword v82, v233, s[62:63]
	s_add_u32 s62, s62, 0x1800
	s_addc_u32 s63, s63, 0
	global_load_dword v83, v233, s[62:63]
	s_add_u32 s62, s62, 0x1800
	s_addc_u32 s63, s63, 0
	global_load_dword v84, v233, s[62:63]
	s_add_u32 s62, s62, 0x1800
	s_addc_u32 s63, s63, 0
	global_load_dword v85, v233, s[62:63]
	s_add_u32 s62, s62, 0x1800
	s_addc_u32 s63, s63, 0
	global_load_dword v86, v233, s[62:63]
	s_add_u32 s62, s62, 0x1800
	s_addc_u32 s63, s63, 0
	global_load_dword v87, v233, s[62:63]
	s_add_u32 s62, s62, 0x1800
	s_addc_u32 s63, s63, 0
	global_load_dword v88, v233, s[62:63]
	s_add_u32 s62, s62, 0x1800
	s_addc_u32 s63, s63, 0
	global_load_dword v89, v233, s[62:63]
	s_add_u32 s62, s62, 0x1800
	s_addc_u32 s63, s63, 0
	global_load_dword v90, v233, s[62:63]
	s_add_u32 s62, s62, 0x1800
	s_addc_u32 s63, s63, 0
	global_load_dword v91, v233, s[62:63]
	s_add_u32 s62, s62, 0x1800
	s_addc_u32 s63, s63, 0
	global_load_dword v92, v233, s[62:63]
	s_add_u32 s62, s62, 0x1800
	s_addc_u32 s63, s63, 0
	global_load_dword v93, v233, s[62:63]
	s_add_u32 s62, s62, 0x1800
	s_addc_u32 s63, s63, 0
	global_load_dword v94, v233, s[62:63]
	s_add_u32 s62, s62, 0x1800
	s_addc_u32 s63, s63, 0
	global_load_dword v95, v233, s[62:63]
	s_add_u32 s62, s62, 0x1800
	s_addc_u32 s63, s63, 0
	global_load_dword v96, v233, s[62:63]
	s_add_u32 s62, s62, 0x1800
	s_addc_u32 s63, s63, 0
	global_load_dword v97, v233, s[62:63]
	s_add_u32 s62, s62, 0x1800
	s_addc_u32 s63, s63, 0
	s_mov_b64 s[44:45], s[62:63]
	s_mov_b32 s62, -1
	s_mov_b32 s63, 0xffff
	s_mov_b64 exec, s[62:63]
	v_lshlrev_b32_e32 v64, 16, v66
	v_and_b32_e32 v65, 0xffff0000, v66
	v_fma_f32 v242, v58, v48, v56
	v_fma_f32 v243, v59, v49, v57
	v_lshlrev_b32_e32 v58, 16, v67
	v_and_b32_e32 v59, 0xffff0000, v67
	v_fma_f32 v244, v60, v48, v56
	v_fma_f32 v245, v61, v49, v57
	v_fma_f32 v242, v60, v50, v242
	v_fma_f32 v243, v61, v51, v243
	v_fma_f32 v244, v62, v50, v244
	v_fma_f32 v245, v63, v51, v245
	v_fma_f32 v242, v62, v52, v242
	v_fma_f32 v243, v63, v53, v243
	v_fma_f32 v244, v64, v52, v244
	v_fma_f32 v245, v65, v53, v245
	v_fma_f32 v242, v64, v54, v242
	v_fma_f32 v243, v65, v55, v243
	v_fma_f32 v244, v58, v54, v244
	v_fma_f32 v245, v59, v55, v245
	ds_write_b64 v226, v[242:243] offset:0
	v_cvt_pk_bf16_f32 v246, v242, v243
	ds_write_b64 v226, v[244:245] offset:400
	v_cvt_pk_bf16_f32 v247, v244, v245
	ds_write_b32 v227, v246 offset:0
	ds_write_b32 v227, v247 offset:208
	v_lshlrev_b32_e32 v60, 16, v68
	v_and_b32_e32 v61, 0xffff0000, v68
	v_fma_f32 v242, v62, v48, v56
	v_fma_f32 v243, v63, v49, v57
	v_lshlrev_b32_e32 v62, 16, v69
	v_and_b32_e32 v63, 0xffff0000, v69
	v_fma_f32 v244, v64, v48, v56
	v_fma_f32 v245, v65, v49, v57
	v_fma_f32 v242, v64, v50, v242
	v_fma_f32 v243, v65, v51, v243
	v_fma_f32 v244, v58, v50, v244
	v_fma_f32 v245, v59, v51, v245
	v_fma_f32 v242, v58, v52, v242
	v_fma_f32 v243, v59, v53, v243
	v_fma_f32 v244, v60, v52, v244
	v_fma_f32 v245, v61, v53, v245
	v_fma_f32 v242, v60, v54, v242
	v_fma_f32 v243, v61, v55, v243
	v_fma_f32 v244, v62, v54, v244
	v_fma_f32 v245, v63, v55, v245
	ds_write_b64 v226, v[242:243] offset:800
	v_cvt_pk_bf16_f32 v246, v242, v243
	ds_write_b64 v226, v[244:245] offset:1200
	v_cvt_pk_bf16_f32 v247, v244, v245
	ds_write_b32 v227, v246 offset:416
	ds_write_b32 v227, v247 offset:624
	v_lshlrev_b32_e32 v64, 16, v70
	v_and_b32_e32 v65, 0xffff0000, v70
	v_fma_f32 v242, v58, v48, v56
	v_fma_f32 v243, v59, v49, v57
	v_lshlrev_b32_e32 v58, 16, v71
	v_and_b32_e32 v59, 0xffff0000, v71
	v_fma_f32 v244, v60, v48, v56
	v_fma_f32 v245, v61, v49, v57
	v_fma_f32 v242, v60, v50, v242
	v_fma_f32 v243, v61, v51, v243
	v_fma_f32 v244, v62, v50, v244
	v_fma_f32 v245, v63, v51, v245
	v_fma_f32 v242, v62, v52, v242
	v_fma_f32 v243, v63, v53, v243
	v_fma_f32 v244, v64, v52, v244
	v_fma_f32 v245, v65, v53, v245
	v_fma_f32 v242, v64, v54, v242
	v_fma_f32 v243, v65, v55, v243
	v_fma_f32 v244, v58, v54, v244
	v_fma_f32 v245, v59, v55, v245
	ds_write_b64 v226, v[242:243] offset:1600
	v_cvt_pk_bf16_f32 v246, v242, v243
	ds_write_b64 v226, v[244:245] offset:2000
	v_cvt_pk_bf16_f32 v247, v244, v245
	ds_write_b32 v227, v246 offset:832
	ds_write_b32 v227, v247 offset:1040
	v_lshlrev_b32_e32 v60, 16, v72
	v_and_b32_e32 v61, 0xffff0000, v72
	v_fma_f32 v242, v62, v48, v56
	v_fma_f32 v243, v63, v49, v57
	v_lshlrev_b32_e32 v62, 16, v73
	v_and_b32_e32 v63, 0xffff0000, v73
	v_fma_f32 v244, v64, v48, v56
	v_fma_f32 v245, v65, v49, v57
	v_fma_f32 v242, v64, v50, v242
	v_fma_f32 v243, v65, v51, v243
	v_fma_f32 v244, v58, v50, v244
	v_fma_f32 v245, v59, v51, v245
	v_fma_f32 v242, v58, v52, v242
	v_fma_f32 v243, v59, v53, v243
	v_fma_f32 v244, v60, v52, v244
	v_fma_f32 v245, v61, v53, v245
	v_fma_f32 v242, v60, v54, v242
	v_fma_f32 v243, v61, v55, v243
	v_fma_f32 v244, v62, v54, v244
	v_fma_f32 v245, v63, v55, v245
	ds_write_b64 v226, v[242:243] offset:2400
	v_cvt_pk_bf16_f32 v246, v242, v243
	ds_write_b64 v226, v[244:245] offset:2800
	v_cvt_pk_bf16_f32 v247, v244, v245
	ds_write_b32 v227, v246 offset:1248
	ds_write_b32 v227, v247 offset:1456
	v_lshlrev_b32_e32 v64, 16, v74
	v_and_b32_e32 v65, 0xffff0000, v74
	v_fma_f32 v242, v58, v48, v56
	v_fma_f32 v243, v59, v49, v57
	v_lshlrev_b32_e32 v58, 16, v75
	v_and_b32_e32 v59, 0xffff0000, v75
	v_fma_f32 v244, v60, v48, v56
	v_fma_f32 v245, v61, v49, v57
	v_fma_f32 v242, v60, v50, v242
	v_fma_f32 v243, v61, v51, v243
	v_fma_f32 v244, v62, v50, v244
	v_fma_f32 v245, v63, v51, v245
	v_fma_f32 v242, v62, v52, v242
	v_fma_f32 v243, v63, v53, v243
	v_fma_f32 v244, v64, v52, v244
	v_fma_f32 v245, v65, v53, v245
	v_fma_f32 v242, v64, v54, v242
	v_fma_f32 v243, v65, v55, v243
	v_fma_f32 v244, v58, v54, v244
	v_fma_f32 v245, v59, v55, v245
	ds_write_b64 v226, v[242:243] offset:3200
	v_cvt_pk_bf16_f32 v246, v242, v243
	ds_write_b64 v226, v[244:245] offset:3600
	v_cvt_pk_bf16_f32 v247, v244, v245
	ds_write_b32 v227, v246 offset:1664
	ds_write_b32 v227, v247 offset:1872
	v_lshlrev_b32_e32 v60, 16, v76
	v_and_b32_e32 v61, 0xffff0000, v76
	v_fma_f32 v242, v62, v48, v56
	v_fma_f32 v243, v63, v49, v57
	v_lshlrev_b32_e32 v62, 16, v77
	v_and_b32_e32 v63, 0xffff0000, v77
	v_fma_f32 v244, v64, v48, v56
	v_fma_f32 v245, v65, v49, v57
	v_fma_f32 v242, v64, v50, v242
	v_fma_f32 v243, v65, v51, v243
	v_fma_f32 v244, v58, v50, v244
	v_fma_f32 v245, v59, v51, v245
	v_fma_f32 v242, v58, v52, v242
	v_fma_f32 v243, v59, v53, v243
	v_fma_f32 v244, v60, v52, v244
	v_fma_f32 v245, v61, v53, v245
	v_fma_f32 v242, v60, v54, v242
	v_fma_f32 v243, v61, v55, v243
	v_fma_f32 v244, v62, v54, v244
	v_fma_f32 v245, v63, v55, v245
	ds_write_b64 v226, v[242:243] offset:4000
	v_cvt_pk_bf16_f32 v246, v242, v243
	ds_write_b64 v226, v[244:245] offset:4400
	v_cvt_pk_bf16_f32 v247, v244, v245
	ds_write_b32 v227, v246 offset:2080
	ds_write_b32 v227, v247 offset:2288
	v_lshlrev_b32_e32 v64, 16, v78
	v_and_b32_e32 v65, 0xffff0000, v78
	v_fma_f32 v242, v58, v48, v56
	v_fma_f32 v243, v59, v49, v57
	v_lshlrev_b32_e32 v58, 16, v79
	v_and_b32_e32 v59, 0xffff0000, v79
	v_fma_f32 v244, v60, v48, v56
	v_fma_f32 v245, v61, v49, v57
	v_fma_f32 v242, v60, v50, v242
	v_fma_f32 v243, v61, v51, v243
	v_fma_f32 v244, v62, v50, v244
	v_fma_f32 v245, v63, v51, v245
	v_fma_f32 v242, v62, v52, v242
	v_fma_f32 v243, v63, v53, v243
	v_fma_f32 v244, v64, v52, v244
	v_fma_f32 v245, v65, v53, v245
	v_fma_f32 v242, v64, v54, v242
	v_fma_f32 v243, v65, v55, v243
	v_fma_f32 v244, v58, v54, v244
	v_fma_f32 v245, v59, v55, v245
	ds_write_b64 v226, v[242:243] offset:4800
	v_cvt_pk_bf16_f32 v246, v242, v243
	ds_write_b64 v226, v[244:245] offset:5200
	v_cvt_pk_bf16_f32 v247, v244, v245
	ds_write_b32 v227, v246 offset:2496
	ds_write_b32 v227, v247 offset:2704
	v_lshlrev_b32_e32 v60, 16, v80
	v_and_b32_e32 v61, 0xffff0000, v80
	v_fma_f32 v242, v62, v48, v56
	v_fma_f32 v243, v63, v49, v57
	v_lshlrev_b32_e32 v62, 16, v81
	v_and_b32_e32 v63, 0xffff0000, v81
	v_fma_f32 v244, v64, v48, v56
	v_fma_f32 v245, v65, v49, v57
	v_fma_f32 v242, v64, v50, v242
	v_fma_f32 v243, v65, v51, v243
	v_fma_f32 v244, v58, v50, v244
	v_fma_f32 v245, v59, v51, v245
	v_fma_f32 v242, v58, v52, v242
	v_fma_f32 v243, v59, v53, v243
	v_fma_f32 v244, v60, v52, v244
	v_fma_f32 v245, v61, v53, v245
	v_fma_f32 v242, v60, v54, v242
	v_fma_f32 v243, v61, v55, v243
	v_fma_f32 v244, v62, v54, v244
	v_fma_f32 v245, v63, v55, v245
	ds_write_b64 v226, v[242:243] offset:5600
	v_cvt_pk_bf16_f32 v246, v242, v243
	ds_write_b64 v226, v[244:245] offset:6000
	v_cvt_pk_bf16_f32 v247, v244, v245
	ds_write_b32 v227, v246 offset:2912
	ds_write_b32 v227, v247 offset:3120
	s_mov_b64 exec, -1
	s_waitcnt lgkmcnt(0)
	ds_read_b128 v[98:101], v228 offset:0
	ds_read_b128 v[102:105], v228 offset:64
	ds_read_b128 v[106:109], v228 offset:128
	ds_read_b128 v[110:113], v229 offset:0
	ds_read_b128 v[122:125], v229 offset:19968
	ds_read_b128 v[114:117], v229 offset:64
	ds_read_b128 v[126:129], v229 offset:20032
	ds_read_b128 v[118:121], v229 offset:128
	ds_read_b128 v[130:133], v229 offset:20096
	ds_read_b128 v[150:153], v230 offset:0
	ds_read_b128 v[154:157], v230 offset:384
	ds_read_b128 v[158:161], v230 offset:768
	ds_read_b128 v[162:165], v231 offset:0
	s_waitcnt lgkmcnt(0)
	v_mfma_f32_16x16x32_bf16 v[134:137], v[110:113], v[98:101], 0
	v_mfma_f32_16x16x32_bf16 v[138:141], v[122:125], v[98:101], 0
	v_mfma_f32_16x16x32_bf16 v[134:137], v[114:117], v[102:105], v[134:137]
	v_mfma_f32_16x16x32_bf16 v[138:141], v[126:129], v[102:105], v[138:141]
	v_mfma_f32_16x16x32_bf16 v[134:137], v[118:121], v[106:109], v[134:137]
	v_mfma_f32_16x16x32_bf16 v[138:141], v[130:133], v[106:109], v[138:141]
	ds_read_b128 v[110:113], v229 offset:3328
	ds_read_b128 v[122:125], v229 offset:23296
	ds_read_b128 v[114:117], v229 offset:3392
	ds_read_b128 v[126:129], v229 offset:23360
	ds_read_b128 v[118:121], v229 offset:3456
	ds_read_b128 v[130:133], v229 offset:23424
	s_nop 7
	s_nop 7
	v_fmamk_f32 v166, v134, 0xbfb8aa3b, v150
	v_fmamk_f32 v204, v135, 0xbfb8aa3b, v151
	v_fmamk_f32 v210, v136, 0xbfb8aa3b, v152
	v_fmamk_f32 v216, v137, 0xbfb8aa3b, v153
	v_fmamk_f32 v167, v138, 0xbfb8aa3b, v154
	v_fmamk_f32 v205, v139, 0xbfb8aa3b, v155
	v_fmamk_f32 v211, v140, 0xbfb8aa3b, v156
	v_fmamk_f32 v217, v141, 0xbfb8aa3b, v157
	v_exp_f32_e32 v166, v166
	v_exp_f32_e32 v204, v204
	v_exp_f32_e32 v210, v210
	v_exp_f32_e32 v216, v216
	v_exp_f32_e32 v167, v167
	v_exp_f32_e32 v205, v205
	v_exp_f32_e32 v211, v211
	v_exp_f32_e32 v217, v217
	v_add_f32_e32 v166, 1.0, v166
	v_add_f32_e32 v204, 1.0, v204
	v_add_f32_e32 v210, 1.0, v210
	v_add_f32_e32 v216, 1.0, v216
	v_add_f32_e32 v167, 1.0, v167
	v_add_f32_e32 v205, 1.0, v205
	v_add_f32_e32 v211, 1.0, v211
	v_add_f32_e32 v217, 1.0, v217
	v_rcp_f32_e32 v166, v166
	v_rcp_f32_e32 v204, v204
	v_rcp_f32_e32 v210, v210
	v_rcp_f32_e32 v216, v216
	v_rcp_f32_e32 v167, v167
	v_rcp_f32_e32 v205, v205
	v_rcp_f32_e32 v211, v211
	v_rcp_f32_e32 v217, v217
	v_mul_f32_e32 v168, v158, v166
	v_mul_f32_e32 v206, v159, v204
	v_mul_f32_e32 v212, v160, v210
	v_mul_f32_e32 v218, v161, v216
	v_mul_f32_e32 v167, v162, v167
	v_mul_f32_e32 v205, v163, v205
	v_mul_f32_e32 v211, v164, v211
	v_mul_f32_e32 v217, v165, v217
	v_exp_f32_e32 v166, v168
	v_exp_f32_e32 v204, v206
	v_exp_f32_e32 v210, v212
	v_exp_f32_e32 v216, v218
	v_fmaak_f32 v170, v168, v248, 0xbe1d955b
	v_fmaak_f32 v208, v206, v248, 0xbe1d955b
	v_fmaak_f32 v214, v212, v248, 0xbe1d955b
	v_fmaak_f32 v220, v218, v248, 0xbe1d955b
	v_fmaak_f32 v170, v168, v170, 0xbee35847
	v_fmaak_f32 v208, v206, v208, 0xbee35847
	v_fmaak_f32 v214, v212, v214, 0xbee35847
	v_fmaak_f32 v220, v218, v220, 0xbee35847
	v_min3_f32 v169, v168, v206, v212
	v_fmaak_f32 v170, v168, v170, 0xbf75fdf0
	v_fmaak_f32 v208, v206, v208, 0xbf75fdf0
	v_fmaak_f32 v214, v212, v214, 0xbf75fdf0
	v_fmaak_f32 v220, v218, v220, 0xbf75fdf0
	v_min_f32_e32 v169, v169, v218
	v_fmaak_f32 v170, v168, v170, 0xbfb17218
	v_fmaak_f32 v208, v206, v208, 0xbfb17218
	v_fmaak_f32 v214, v212, v214, 0xbfb17218
	v_fmaak_f32 v220, v218, v220, 0xbfb17218
	v_cmp_nlt_f32_e32 vcc, 0xbe38aa3b, v169
	v_mul_f32_e32 v170, v170, v168
	v_mul_f32_e32 v208, v208, v206
	v_mul_f32_e32 v214, v214, v212
	v_mul_f32_e32 v220, v220, v218
	s_cbranch_vccnz .Lscan2_far0
.Lscan2_back0:
	v_sqrt_f32_e32 v170, v170
	v_sqrt_f32_e32 v208, v208
	v_sqrt_f32_e32 v214, v214
	v_sqrt_f32_e32 v220, v220
	v_mul_f32_e32 v167, v167, v170
	v_mul_f32_e32 v205, v205, v208
	v_mul_f32_e32 v211, v211, v214
	v_mul_f32_e32 v217, v217, v220
	ds_read_b128 v[150:153], v230 offset:64
	ds_read_b128 v[154:157], v230 offset:448
	ds_read_b128 v[158:161], v230 offset:832
	ds_read_b128 v[162:165], v231 offset:64
	s_waitcnt lgkmcnt(0)
	v_mfma_f32_16x16x32_bf16 v[142:145], v[110:113], v[98:101], 0
	v_mfma_f32_16x16x32_bf16 v[146:149], v[122:125], v[98:101], 0
	v_mfma_f32_16x16x32_bf16 v[142:145], v[114:117], v[102:105], v[142:145]
	v_mfma_f32_16x16x32_bf16 v[146:149], v[126:129], v[102:105], v[146:149]
	v_mfma_f32_16x16x32_bf16 v[142:145], v[118:121], v[106:109], v[142:145]
	v_mfma_f32_16x16x32_bf16 v[146:149], v[130:133], v[106:109], v[146:149]
	v_fmac_f32_dpp v167, v167, v166 row_shr:1 row_mask:0xf bank_mask:0xf bound_ctrl:1
	v_fmac_f32_dpp v205, v205, v204 row_shr:1 row_mask:0xf bank_mask:0xf bound_ctrl:1
	v_fmac_f32_dpp v211, v211, v210 row_shr:1 row_mask:0xf bank_mask:0xf bound_ctrl:1
	v_fmac_f32_dpp v217, v217, v216 row_shr:1 row_mask:0xf bank_mask:0xf bound_ctrl:1
	v_mul_f32_dpp v166, v166, v166 row_shr:1 row_mask:0xf bank_mask:0xf
	v_mul_f32_dpp v204, v204, v204 row_shr:1 row_mask:0xf bank_mask:0xf
	v_mul_f32_dpp v210, v210, v210 row_shr:1 row_mask:0xf bank_mask:0xf
	v_mul_f32_dpp v216, v216, v216 row_shr:1 row_mask:0xf bank_mask:0xf
	v_fmac_f32_dpp v167, v167, v166 row_shr:2 row_mask:0xf bank_mask:0xf bound_ctrl:1
	v_fmac_f32_dpp v205, v205, v204 row_shr:2 row_mask:0xf bank_mask:0xf bound_ctrl:1
	v_fmac_f32_dpp v211, v211, v210 row_shr:2 row_mask:0xf bank_mask:0xf bound_ctrl:1
	v_fmac_f32_dpp v217, v217, v216 row_shr:2 row_mask:0xf bank_mask:0xf bound_ctrl:1
	v_mul_f32_dpp v166, v166, v166 row_shr:2 row_mask:0xf bank_mask:0xf
	v_mul_f32_dpp v204, v204, v204 row_shr:2 row_mask:0xf bank_mask:0xf
	v_mul_f32_dpp v210, v210, v210 row_shr:2 row_mask:0xf bank_mask:0xf
	v_mul_f32_dpp v216, v216, v216 row_shr:2 row_mask:0xf bank_mask:0xf
	v_fmac_f32_dpp v167, v167, v166 row_shr:4 row_mask:0xf bank_mask:0xf bound_ctrl:1
	v_fmac_f32_dpp v205, v205, v204 row_shr:4 row_mask:0xf bank_mask:0xf bound_ctrl:1
	v_fmac_f32_dpp v211, v211, v210 row_shr:4 row_mask:0xf bank_mask:0xf bound_ctrl:1
	v_fmac_f32_dpp v217, v217, v216 row_shr:4 row_mask:0xf bank_mask:0xf bound_ctrl:1
	v_mul_f32_dpp v166, v166, v166 row_shr:4 row_mask:0xf bank_mask:0xf
	v_mul_f32_dpp v204, v204, v204 row_shr:4 row_mask:0xf bank_mask:0xf
	v_mul_f32_dpp v210, v210, v210 row_shr:4 row_mask:0xf bank_mask:0xf
	v_mul_f32_dpp v216, v216, v216 row_shr:4 row_mask:0xf bank_mask:0xf
	v_fmac_f32_dpp v167, v167, v166 row_shr:8 row_mask:0xf bank_mask:0xf bound_ctrl:1
	v_fmac_f32_dpp v205, v205, v204 row_shr:8 row_mask:0xf bank_mask:0xf bound_ctrl:1
	v_fmac_f32_dpp v211, v211, v210 row_shr:8 row_mask:0xf bank_mask:0xf bound_ctrl:1
	v_fmac_f32_dpp v217, v217, v216 row_shr:8 row_mask:0xf bank_mask:0xf bound_ctrl:1
	v_mul_f32_dpp v166, v166, v166 row_shr:8 row_mask:0xf bank_mask:0xf
	v_mul_f32_dpp v204, v204, v204 row_shr:8 row_mask:0xf bank_mask:0xf
	v_mul_f32_dpp v210, v210, v210 row_shr:8 row_mask:0xf bank_mask:0xf
	v_mul_f32_dpp v216, v216, v216 row_shr:8 row_mask:0xf bank_mask:0xf
	v_fma_f32 v168, v166, v0, v167
	v_fma_f32 v206, v204, v1, v205
	v_fma_f32 v212, v210, v2, v211
	v_fma_f32 v218, v216, v3, v217
	ds_bpermute_b32 v0, v232, v168
	ds_bpermute_b32 v1, v232, v206
	ds_bpermute_b32 v2, v232, v212
	ds_bpermute_b32 v3, v232, v218
	s_waitcnt vmcnt(21)
	v_lshlrev_b32_e32 v169, 16, v24
	v_and_b32_e32 v207, 0xffff0000, v24
	v_lshlrev_b32_e32 v213, 16, v25
	v_and_b32_e32 v219, 0xffff0000, v25
	v_mul_f32_e32 v170, v169, v169
	v_mul_f32_e32 v208, v207, v207
	v_mul_f32_e32 v214, v213, v213
	v_mul_f32_e32 v220, v219, v219
	v_fmaak_f32 v170, v170, v249, 0xc0135761
	v_fmaak_f32 v208, v208, v249, 0xc0135761
	v_fmaak_f32 v214, v214, v249, 0xc0135761
	v_fmaak_f32 v220, v220, v249, 0xc0135761
	v_mul_f32_e32 v170, v169, v170
	v_mul_f32_e32 v208, v207, v208
	v_mul_f32_e32 v214, v213, v214
	v_mul_f32_e32 v220, v219, v220
	v_exp_f32_e32 v170, v170
	v_exp_f32_e32 v208, v208
	v_exp_f32_e32 v214, v214
	v_exp_f32_e32 v220, v220
	v_add_f32_e32 v170, 1.0, v170
	v_add_f32_e32 v208, 1.0, v208
	v_add_f32_e32 v214, 1.0, v214
	v_add_f32_e32 v220, 1.0, v220
	v_rcp_f32_e32 v170, v170
	v_rcp_f32_e32 v208, v208
	v_rcp_f32_e32 v214, v214
	v_rcp_f32_e32 v220, v220
	v_mul_f32_e32 v170, v169, v170
	v_mul_f32_e32 v208, v207, v208
	v_mul_f32_e32 v214, v213, v214
	v_mul_f32_e32 v220, v219, v220
	v_mul_f32_e32 v170, v170, v168
	v_mul_f32_e32 v208, v208, v206
	v_mul_f32_e32 v214, v214, v212
	v_mul_f32_e32 v220, v220, v218
	v_cvt_pk_bf16_f32 v242, v170, v208
	v_cvt_pk_bf16_f32 v243, v214, v220
	global_store_dwordx2 v236, v[242:243], s[100:101] offset:0
	ds_read_b128 v[110:113], v229 offset:6656
	ds_read_b128 v[122:125], v229 offset:26624
	ds_read_b128 v[114:117], v229 offset:6720
	ds_read_b128 v[126:129], v229 offset:26688
	ds_read_b128 v[118:121], v229 offset:6784
	ds_read_b128 v[130:133], v229 offset:26752
	v_fmamk_f32 v166, v142, 0xbfb8aa3b, v150
	v_fmamk_f32 v204, v143, 0xbfb8aa3b, v151
	v_fmamk_f32 v210, v144, 0xbfb8aa3b, v152
	v_fmamk_f32 v216, v145, 0xbfb8aa3b, v153
	v_fmamk_f32 v167, v146, 0xbfb8aa3b, v154
	v_fmamk_f32 v205, v147, 0xbfb8aa3b, v155
	v_fmamk_f32 v211, v148, 0xbfb8aa3b, v156
	v_fmamk_f32 v217, v149, 0xbfb8aa3b, v157
	v_exp_f32_e32 v166, v166
	v_exp_f32_e32 v204, v204
	v_exp_f32_e32 v210, v210
	v_exp_f32_e32 v216, v216
	v_exp_f32_e32 v167, v167
	v_exp_f32_e32 v205, v205
	v_exp_f32_e32 v211, v211
	v_exp_f32_e32 v217, v217
	v_add_f32_e32 v166, 1.0, v166
	v_add_f32_e32 v204, 1.0, v204
	v_add_f32_e32 v210, 1.0, v210
	v_add_f32_e32 v216, 1.0, v216
	v_add_f32_e32 v167, 1.0, v167
	v_add_f32_e32 v205, 1.0, v205
	v_add_f32_e32 v211, 1.0, v211
	v_add_f32_e32 v217, 1.0, v217
	v_rcp_f32_e32 v166, v166
	v_rcp_f32_e32 v204, v204
	v_rcp_f32_e32 v210, v210
	v_rcp_f32_e32 v216, v216
	v_rcp_f32_e32 v167, v167
	v_rcp_f32_e32 v205, v205
	v_rcp_f32_e32 v211, v211
	v_rcp_f32_e32 v217, v217
	v_mul_f32_e32 v168, v158, v166
	v_mul_f32_e32 v206, v159, v204
	v_mul_f32_e32 v212, v160, v210
	v_mul_f32_e32 v218, v161, v216
	v_mul_f32_e32 v167, v162, v167
	v_mul_f32_e32 v205, v163, v205
	v_mul_f32_e32 v211, v164, v211
	v_mul_f32_e32 v217, v165, v217
	v_exp_f32_e32 v166, v168
	v_exp_f32_e32 v204, v206
	v_exp_f32_e32 v210, v212
	v_exp_f32_e32 v216, v218
	v_fmaak_f32 v170, v168, v248, 0xbe1d955b
	v_fmaak_f32 v208, v206, v248, 0xbe1d955b
	v_fmaak_f32 v214, v212, v248, 0xbe1d955b
	v_fmaak_f32 v220, v218, v248, 0xbe1d955b
	v_fmaak_f32 v170, v168, v170, 0xbee35847
	v_fmaak_f32 v208, v206, v208, 0xbee35847
	v_fmaak_f32 v214, v212, v214, 0xbee35847
	v_fmaak_f32 v220, v218, v220, 0xbee35847
	v_min3_f32 v169, v168, v206, v212
	v_fmaak_f32 v170, v168, v170, 0xbf75fdf0
	v_fmaak_f32 v208, v206, v208, 0xbf75fdf0
	v_fmaak_f32 v214, v212, v214, 0xbf75fdf0
	v_fmaak_f32 v220, v218, v220, 0xbf75fdf0
	v_min_f32_e32 v169, v169, v218
	v_fmaak_f32 v170, v168, v170, 0xbfb17218
	v_fmaak_f32 v208, v206, v208, 0xbfb17218
	v_fmaak_f32 v214, v212, v214, 0xbfb17218
	v_fmaak_f32 v220, v218, v220, 0xbfb17218
	v_cmp_nlt_f32_e32 vcc, 0xbe38aa3b, v169
	v_mul_f32_e32 v170, v170, v168
	v_mul_f32_e32 v208, v208, v206
	v_mul_f32_e32 v214, v214, v212
	v_mul_f32_e32 v220, v220, v218
	s_cbranch_vccnz .Lscan2_far1
.Lscan2_back1:
	v_sqrt_f32_e32 v170, v170
	v_sqrt_f32_e32 v208, v208
	v_sqrt_f32_e32 v214, v214
	v_sqrt_f32_e32 v220, v220
	v_mul_f32_e32 v167, v167, v170
	v_mul_f32_e32 v205, v205, v208
	v_mul_f32_e32 v211, v211, v214
	v_mul_f32_e32 v217, v217, v220
	ds_read_b128 v[150:153], v230 offset:128
	ds_read_b128 v[154:157], v230 offset:512
	ds_read_b128 v[158:161], v230 offset:896
	ds_read_b128 v[162:165], v231 offset:128
	s_waitcnt lgkmcnt(0)
	v_mfma_f32_16x16x32_bf16 v[134:137], v[110:113], v[98:101], 0
	v_mfma_f32_16x16x32_bf16 v[138:141], v[122:125], v[98:101], 0
	v_mfma_f32_16x16x32_bf16 v[134:137], v[114:117], v[102:105], v[134:137]
	v_mfma_f32_16x16x32_bf16 v[138:141], v[126:129], v[102:105], v[138:141]
	v_mfma_f32_16x16x32_bf16 v[134:137], v[118:121], v[106:109], v[134:137]
	v_mfma_f32_16x16x32_bf16 v[138:141], v[130:133], v[106:109], v[138:141]
	v_fmac_f32_dpp v167, v167, v166 row_shr:1 row_mask:0xf bank_mask:0xf bound_ctrl:1
	v_fmac_f32_dpp v205, v205, v204 row_shr:1 row_mask:0xf bank_mask:0xf bound_ctrl:1
	v_fmac_f32_dpp v211, v211, v210 row_shr:1 row_mask:0xf bank_mask:0xf bound_ctrl:1
	v_fmac_f32_dpp v217, v217, v216 row_shr:1 row_mask:0xf bank_mask:0xf bound_ctrl:1
	v_mul_f32_dpp v166, v166, v166 row_shr:1 row_mask:0xf bank_mask:0xf
	v_mul_f32_dpp v204, v204, v204 row_shr:1 row_mask:0xf bank_mask:0xf
	v_mul_f32_dpp v210, v210, v210 row_shr:1 row_mask:0xf bank_mask:0xf
	v_mul_f32_dpp v216, v216, v216 row_shr:1 row_mask:0xf bank_mask:0xf
	v_fmac_f32_dpp v167, v167, v166 row_shr:2 row_mask:0xf bank_mask:0xf bound_ctrl:1
	v_fmac_f32_dpp v205, v205, v204 row_shr:2 row_mask:0xf bank_mask:0xf bound_ctrl:1
	v_fmac_f32_dpp v211, v211, v210 row_shr:2 row_mask:0xf bank_mask:0xf bound_ctrl:1
	v_fmac_f32_dpp v217, v217, v216 row_shr:2 row_mask:0xf bank_mask:0xf bound_ctrl:1
	v_mul_f32_dpp v166, v166, v166 row_shr:2 row_mask:0xf bank_mask:0xf
	v_mul_f32_dpp v204, v204, v204 row_shr:2 row_mask:0xf bank_mask:0xf
	v_mul_f32_dpp v210, v210, v210 row_shr:2 row_mask:0xf bank_mask:0xf
	v_mul_f32_dpp v216, v216, v216 row_shr:2 row_mask:0xf bank_mask:0xf
	v_fmac_f32_dpp v167, v167, v166 row_shr:4 row_mask:0xf bank_mask:0xf bound_ctrl:1
	v_fmac_f32_dpp v205, v205, v204 row_shr:4 row_mask:0xf bank_mask:0xf bound_ctrl:1
	v_fmac_f32_dpp v211, v211, v210 row_shr:4 row_mask:0xf bank_mask:0xf bound_ctrl:1
	v_fmac_f32_dpp v217, v217, v216 row_shr:4 row_mask:0xf bank_mask:0xf bound_ctrl:1
	v_mul_f32_dpp v166, v166, v166 row_shr:4 row_mask:0xf bank_mask:0xf
	v_mul_f32_dpp v204, v204, v204 row_shr:4 row_mask:0xf bank_mask:0xf
	v_mul_f32_dpp v210, v210, v210 row_shr:4 row_mask:0xf bank_mask:0xf
	v_mul_f32_dpp v216, v216, v216 row_shr:4 row_mask:0xf bank_mask:0xf
	v_fmac_f32_dpp v167, v167, v166 row_shr:8 row_mask:0xf bank_mask:0xf bound_ctrl:1
	v_fmac_f32_dpp v205, v205, v204 row_shr:8 row_mask:0xf bank_mask:0xf bound_ctrl:1
	v_fmac_f32_dpp v211, v211, v210 row_shr:8 row_mask:0xf bank_mask:0xf bound_ctrl:1
	v_fmac_f32_dpp v217, v217, v216 row_shr:8 row_mask:0xf bank_mask:0xf bound_ctrl:1
	v_mul_f32_dpp v166, v166, v166 row_shr:8 row_mask:0xf bank_mask:0xf
	v_mul_f32_dpp v204, v204, v204 row_shr:8 row_mask:0xf bank_mask:0xf
	v_mul_f32_dpp v210, v210, v210 row_shr:8 row_mask:0xf bank_mask:0xf
	v_mul_f32_dpp v216, v216, v216 row_shr:8 row_mask:0xf bank_mask:0xf
	v_fma_f32 v168, v166, v4, v167
	v_fma_f32 v206, v204, v5, v205
	v_fma_f32 v212, v210, v6, v211
	v_fma_f32 v218, v216, v7, v217
	ds_bpermute_b32 v4, v232, v168
	ds_bpermute_b32 v5, v232, v206
	ds_bpermute_b32 v6, v232, v212
	ds_bpermute_b32 v7, v232, v218
	s_waitcnt vmcnt(21)
	v_lshlrev_b32_e32 v169, 16, v26
	v_and_b32_e32 v207, 0xffff0000, v26
	v_lshlrev_b32_e32 v213, 16, v27
	v_and_b32_e32 v219, 0xffff0000, v27
	v_mul_f32_e32 v170, v169, v169
	v_mul_f32_e32 v208, v207, v207
	v_mul_f32_e32 v214, v213, v213
	v_mul_f32_e32 v220, v219, v219
	v_fmaak_f32 v170, v170, v249, 0xc0135761
	v_fmaak_f32 v208, v208, v249, 0xc0135761
	v_fmaak_f32 v214, v214, v249, 0xc0135761
	v_fmaak_f32 v220, v220, v249, 0xc0135761
	v_mul_f32_e32 v170, v169, v170
	v_mul_f32_e32 v208, v207, v208
	v_mul_f32_e32 v214, v213, v214
	v_mul_f32_e32 v220, v219, v220
	v_exp_f32_e32 v170, v170
	v_exp_f32_e32 v208, v208
	v_exp_f32_e32 v214, v214
	v_exp_f32_e32 v220, v220
	v_add_f32_e32 v170, 1.0, v170
	v_add_f32_e32 v208, 1.0, v208
	v_add_f32_e32 v214, 1.0, v214
	v_add_f32_e32 v220, 1.0, v220
	v_rcp_f32_e32 v170, v170
	v_rcp_f32_e32 v208, v208
	v_rcp_f32_e32 v214, v214
	v_rcp_f32_e32 v220, v220
	v_mul_f32_e32 v170, v169, v170
	v_mul_f32_e32 v208, v207, v208
	v_mul_f32_e32 v214, v213, v214
	v_mul_f32_e32 v220, v219, v220
	v_mul_f32_e32 v170, v170, v168
	v_mul_f32_e32 v208, v208, v206
	v_mul_f32_e32 v214, v214, v212
	v_mul_f32_e32 v220, v220, v218
	v_cvt_pk_bf16_f32 v242, v170, v208
	v_cvt_pk_bf16_f32 v243, v214, v220
	global_store_dwordx2 v236, v[242:243], s[100:101] offset:32
	ds_read_b128 v[110:113], v229 offset:9984
	ds_read_b128 v[122:125], v229 offset:29952
	ds_read_b128 v[114:117], v229 offset:10048
	ds_read_b128 v[126:129], v229 offset:30016
	ds_read_b128 v[118:121], v229 offset:10112
	ds_read_b128 v[130:133], v229 offset:30080
	v_fmamk_f32 v166, v134, 0xbfb8aa3b, v150
	v_fmamk_f32 v204, v135, 0xbfb8aa3b, v151
	v_fmamk_f32 v210, v136, 0xbfb8aa3b, v152
	v_fmamk_f32 v216, v137, 0xbfb8aa3b, v153
	v_fmamk_f32 v167, v138, 0xbfb8aa3b, v154
	v_fmamk_f32 v205, v139, 0xbfb8aa3b, v155
	v_fmamk_f32 v211, v140, 0xbfb8aa3b, v156
	v_fmamk_f32 v217, v141, 0xbfb8aa3b, v157
	v_exp_f32_e32 v166, v166
	v_exp_f32_e32 v204, v204
	v_exp_f32_e32 v210, v210
	v_exp_f32_e32 v216, v216
	v_exp_f32_e32 v167, v167
	v_exp_f32_e32 v205, v205
	v_exp_f32_e32 v211, v211
	v_exp_f32_e32 v217, v217
	v_add_f32_e32 v166, 1.0, v166
	v_add_f32_e32 v204, 1.0, v204
	v_add_f32_e32 v210, 1.0, v210
	v_add_f32_e32 v216, 1.0, v216
	v_add_f32_e32 v167, 1.0, v167
	v_add_f32_e32 v205, 1.0, v205
	v_add_f32_e32 v211, 1.0, v211
	v_add_f32_e32 v217, 1.0, v217
	v_rcp_f32_e32 v166, v166
	v_rcp_f32_e32 v204, v204
	v_rcp_f32_e32 v210, v210
	v_rcp_f32_e32 v216, v216
	v_rcp_f32_e32 v167, v167
	v_rcp_f32_e32 v205, v205
	v_rcp_f32_e32 v211, v211
	v_rcp_f32_e32 v217, v217
	v_mul_f32_e32 v168, v158, v166
	v_mul_f32_e32 v206, v159, v204
	v_mul_f32_e32 v212, v160, v210
	v_mul_f32_e32 v218, v161, v216
	v_mul_f32_e32 v167, v162, v167
	v_mul_f32_e32 v205, v163, v205
	v_mul_f32_e32 v211, v164, v211
	v_mul_f32_e32 v217, v165, v217
	v_exp_f32_e32 v166, v168
	v_exp_f32_e32 v204, v206
	v_exp_f32_e32 v210, v212
	v_exp_f32_e32 v216, v218
	v_fmaak_f32 v170, v168, v248, 0xbe1d955b
	v_fmaak_f32 v208, v206, v248, 0xbe1d955b
	v_fmaak_f32 v214, v212, v248, 0xbe1d955b
	v_fmaak_f32 v220, v218, v248, 0xbe1d955b
	v_fmaak_f32 v170, v168, v170, 0xbee35847
	v_fmaak_f32 v208, v206, v208, 0xbee35847
	v_fmaak_f32 v214, v212, v214, 0xbee35847
	v_fmaak_f32 v220, v218, v220, 0xbee35847
	v_min3_f32 v169, v168, v206, v212
	v_fmaak_f32 v170, v168, v170, 0xbf75fdf0
	v_fmaak_f32 v208, v206, v208, 0xbf75fdf0
	v_fmaak_f32 v214, v212, v214, 0xbf75fdf0
	v_fmaak_f32 v220, v218, v220, 0xbf75fdf0
	v_min_f32_e32 v169, v169, v218
	v_fmaak_f32 v170, v168, v170, 0xbfb17218
	v_fmaak_f32 v208, v206, v208, 0xbfb17218
	v_fmaak_f32 v214, v212, v214, 0xbfb17218
	v_fmaak_f32 v220, v218, v220, 0xbfb17218
	v_cmp_nlt_f32_e32 vcc, 0xbe38aa3b, v169
	v_mul_f32_e32 v170, v170, v168
	v_mul_f32_e32 v208, v208, v206
	v_mul_f32_e32 v214, v214, v212
	v_mul_f32_e32 v220, v220, v218
	s_cbranch_vccnz .Lscan2_far2
.Lscan2_back2:
	v_sqrt_f32_e32 v170, v170
	v_sqrt_f32_e32 v208, v208
	v_sqrt_f32_e32 v214, v214
	v_sqrt_f32_e32 v220, v220
	v_mul_f32_e32 v167, v167, v170
	v_mul_f32_e32 v205, v205, v208
	v_mul_f32_e32 v211, v211, v214
	v_mul_f32_e32 v217, v217, v220
	ds_read_b128 v[150:153], v230 offset:192
	ds_read_b128 v[154:157], v230 offset:576
	ds_read_b128 v[158:161], v230 offset:960
	ds_read_b128 v[162:165], v231 offset:192
	s_waitcnt lgkmcnt(0)
	v_mfma_f32_16x16x32_bf16 v[142:145], v[110:113], v[98:101], 0
	v_mfma_f32_16x16x32_bf16 v[146:149], v[122:125], v[98:101], 0
	v_mfma_f32_16x16x32_bf16 v[142:145], v[114:117], v[102:105], v[142:145]
	v_mfma_f32_16x16x32_bf16 v[146:149], v[126:129], v[102:105], v[146:149]
	v_mfma_f32_16x16x32_bf16 v[142:145], v[118:121], v[106:109], v[142:145]
	v_mfma_f32_16x16x32_bf16 v[146:149], v[130:133], v[106:109], v[146:149]
	v_fmac_f32_dpp v167, v167, v166 row_shr:1 row_mask:0xf bank_mask:0xf bound_ctrl:1
	v_fmac_f32_dpp v205, v205, v204 row_shr:1 row_mask:0xf bank_mask:0xf bound_ctrl:1
	v_fmac_f32_dpp v211, v211, v210 row_shr:1 row_mask:0xf bank_mask:0xf bound_ctrl:1
	v_fmac_f32_dpp v217, v217, v216 row_shr:1 row_mask:0xf bank_mask:0xf bound_ctrl:1
	v_mul_f32_dpp v166, v166, v166 row_shr:1 row_mask:0xf bank_mask:0xf
	v_mul_f32_dpp v204, v204, v204 row_shr:1 row_mask:0xf bank_mask:0xf
	v_mul_f32_dpp v210, v210, v210 row_shr:1 row_mask:0xf bank_mask:0xf
	v_mul_f32_dpp v216, v216, v216 row_shr:1 row_mask:0xf bank_mask:0xf
	v_fmac_f32_dpp v167, v167, v166 row_shr:2 row_mask:0xf bank_mask:0xf bound_ctrl:1
	v_fmac_f32_dpp v205, v205, v204 row_shr:2 row_mask:0xf bank_mask:0xf bound_ctrl:1
	v_fmac_f32_dpp v211, v211, v210 row_shr:2 row_mask:0xf bank_mask:0xf bound_ctrl:1
	v_fmac_f32_dpp v217, v217, v216 row_shr:2 row_mask:0xf bank_mask:0xf bound_ctrl:1
	v_mul_f32_dpp v166, v166, v166 row_shr:2 row_mask:0xf bank_mask:0xf
	v_mul_f32_dpp v204, v204, v204 row_shr:2 row_mask:0xf bank_mask:0xf
	v_mul_f32_dpp v210, v210, v210 row_shr:2 row_mask:0xf bank_mask:0xf
	v_mul_f32_dpp v216, v216, v216 row_shr:2 row_mask:0xf bank_mask:0xf
	v_fmac_f32_dpp v167, v167, v166 row_shr:4 row_mask:0xf bank_mask:0xf bound_ctrl:1
	v_fmac_f32_dpp v205, v205, v204 row_shr:4 row_mask:0xf bank_mask:0xf bound_ctrl:1
	v_fmac_f32_dpp v211, v211, v210 row_shr:4 row_mask:0xf bank_mask:0xf bound_ctrl:1
	v_fmac_f32_dpp v217, v217, v216 row_shr:4 row_mask:0xf bank_mask:0xf bound_ctrl:1
	v_mul_f32_dpp v166, v166, v166 row_shr:4 row_mask:0xf bank_mask:0xf
	v_mul_f32_dpp v204, v204, v204 row_shr:4 row_mask:0xf bank_mask:0xf
	v_mul_f32_dpp v210, v210, v210 row_shr:4 row_mask:0xf bank_mask:0xf
	v_mul_f32_dpp v216, v216, v216 row_shr:4 row_mask:0xf bank_mask:0xf
	v_fmac_f32_dpp v167, v167, v166 row_shr:8 row_mask:0xf bank_mask:0xf bound_ctrl:1
	v_fmac_f32_dpp v205, v205, v204 row_shr:8 row_mask:0xf bank_mask:0xf bound_ctrl:1
	v_fmac_f32_dpp v211, v211, v210 row_shr:8 row_mask:0xf bank_mask:0xf bound_ctrl:1
	v_fmac_f32_dpp v217, v217, v216 row_shr:8 row_mask:0xf bank_mask:0xf bound_ctrl:1
	v_mul_f32_dpp v166, v166, v166 row_shr:8 row_mask:0xf bank_mask:0xf
	v_mul_f32_dpp v204, v204, v204 row_shr:8 row_mask:0xf bank_mask:0xf
	v_mul_f32_dpp v210, v210, v210 row_shr:8 row_mask:0xf bank_mask:0xf
	v_mul_f32_dpp v216, v216, v216 row_shr:8 row_mask:0xf bank_mask:0xf
	v_fma_f32 v168, v166, v8, v167
	v_fma_f32 v206, v204, v9, v205
	v_fma_f32 v212, v210, v10, v211
	v_fma_f32 v218, v216, v11, v217
	ds_bpermute_b32 v8, v232, v168
	ds_bpermute_b32 v9, v232, v206
	ds_bpermute_b32 v10, v232, v212
	ds_bpermute_b32 v11, v232, v218
	s_waitcnt vmcnt(21)
	v_lshlrev_b32_e32 v169, 16, v28
	v_and_b32_e32 v207, 0xffff0000, v28
	v_lshlrev_b32_e32 v213, 16, v29
	v_and_b32_e32 v219, 0xffff0000, v29
	v_mul_f32_e32 v170, v169, v169
	v_mul_f32_e32 v208, v207, v207
	v_mul_f32_e32 v214, v213, v213
	v_mul_f32_e32 v220, v219, v219
	v_fmaak_f32 v170, v170, v249, 0xc0135761
	v_fmaak_f32 v208, v208, v249, 0xc0135761
	v_fmaak_f32 v214, v214, v249, 0xc0135761
	v_fmaak_f32 v220, v220, v249, 0xc0135761
	v_mul_f32_e32 v170, v169, v170
	v_mul_f32_e32 v208, v207, v208
	v_mul_f32_e32 v214, v213, v214
	v_mul_f32_e32 v220, v219, v220
	v_exp_f32_e32 v170, v170
	v_exp_f32_e32 v208, v208
	v_exp_f32_e32 v214, v214
	v_exp_f32_e32 v220, v220
	v_add_f32_e32 v170, 1.0, v170
	v_add_f32_e32 v208, 1.0, v208
	v_add_f32_e32 v214, 1.0, v214
	v_add_f32_e32 v220, 1.0, v220
	v_rcp_f32_e32 v170, v170
	v_rcp_f32_e32 v208, v208
	v_rcp_f32_e32 v214, v214
	v_rcp_f32_e32 v220, v220
	v_mul_f32_e32 v170, v169, v170
	v_mul_f32_e32 v208, v207, v208
	v_mul_f32_e32 v214, v213, v214
	v_mul_f32_e32 v220, v219, v220
	v_mul_f32_e32 v170, v170, v168
	v_mul_f32_e32 v208, v208, v206
	v_mul_f32_e32 v214, v214, v212
	v_mul_f32_e32 v220, v220, v218
	v_cvt_pk_bf16_f32 v242, v170, v208
	v_cvt_pk_bf16_f32 v243, v214, v220
	global_store_dwordx2 v236, v[242:243], s[100:101] offset:64
	ds_read_b128 v[110:113], v229 offset:13312
	ds_read_b128 v[122:125], v229 offset:33280
	ds_read_b128 v[114:117], v229 offset:13376
	ds_read_b128 v[126:129], v229 offset:33344
	ds_read_b128 v[118:121], v229 offset:13440
	ds_read_b128 v[130:133], v229 offset:33408
	v_fmamk_f32 v166, v142, 0xbfb8aa3b, v150
	v_fmamk_f32 v204, v143, 0xbfb8aa3b, v151
	v_fmamk_f32 v210, v144, 0xbfb8aa3b, v152
	v_fmamk_f32 v216, v145, 0xbfb8aa3b, v153
	v_fmamk_f32 v167, v146, 0xbfb8aa3b, v154
	v_fmamk_f32 v205, v147, 0xbfb8aa3b, v155
	v_fmamk_f32 v211, v148, 0xbfb8aa3b, v156
	v_fmamk_f32 v217, v149, 0xbfb8aa3b, v157
	v_exp_f32_e32 v166, v166
	v_exp_f32_e32 v204, v204
	v_exp_f32_e32 v210, v210
	v_exp_f32_e32 v216, v216
	v_exp_f32_e32 v167, v167
	v_exp_f32_e32 v205, v205
	v_exp_f32_e32 v211, v211
	v_exp_f32_e32 v217, v217
	v_add_f32_e32 v166, 1.0, v166
	v_add_f32_e32 v204, 1.0, v204
	v_add_f32_e32 v210, 1.0, v210
	v_add_f32_e32 v216, 1.0, v216
	v_add_f32_e32 v167, 1.0, v167
	v_add_f32_e32 v205, 1.0, v205
	v_add_f32_e32 v211, 1.0, v211
	v_add_f32_e32 v217, 1.0, v217
	v_rcp_f32_e32 v166, v166
	v_rcp_f32_e32 v204, v204
	v_rcp_f32_e32 v210, v210
	v_rcp_f32_e32 v216, v216
	v_rcp_f32_e32 v167, v167
	v_rcp_f32_e32 v205, v205
	v_rcp_f32_e32 v211, v211
	v_rcp_f32_e32 v217, v217
	v_mul_f32_e32 v168, v158, v166
	v_mul_f32_e32 v206, v159, v204
	v_mul_f32_e32 v212, v160, v210
	v_mul_f32_e32 v218, v161, v216
	v_mul_f32_e32 v167, v162, v167
	v_mul_f32_e32 v205, v163, v205
	v_mul_f32_e32 v211, v164, v211
	v_mul_f32_e32 v217, v165, v217
	v_exp_f32_e32 v166, v168
	v_exp_f32_e32 v204, v206
	v_exp_f32_e32 v210, v212
	v_exp_f32_e32 v216, v218
	v_fmaak_f32 v170, v168, v248, 0xbe1d955b
	v_fmaak_f32 v208, v206, v248, 0xbe1d955b
	v_fmaak_f32 v214, v212, v248, 0xbe1d955b
	v_fmaak_f32 v220, v218, v248, 0xbe1d955b
	v_fmaak_f32 v170, v168, v170, 0xbee35847
	v_fmaak_f32 v208, v206, v208, 0xbee35847
	v_fmaak_f32 v214, v212, v214, 0xbee35847
	v_fmaak_f32 v220, v218, v220, 0xbee35847
	v_min3_f32 v169, v168, v206, v212
	v_fmaak_f32 v170, v168, v170, 0xbf75fdf0
	v_fmaak_f32 v208, v206, v208, 0xbf75fdf0
	v_fmaak_f32 v214, v212, v214, 0xbf75fdf0
	v_fmaak_f32 v220, v218, v220, 0xbf75fdf0
	v_min_f32_e32 v169, v169, v218
	v_fmaak_f32 v170, v168, v170, 0xbfb17218
	v_fmaak_f32 v208, v206, v208, 0xbfb17218
	v_fmaak_f32 v214, v212, v214, 0xbfb17218
	v_fmaak_f32 v220, v218, v220, 0xbfb17218
	v_cmp_nlt_f32_e32 vcc, 0xbe38aa3b, v169
	v_mul_f32_e32 v170, v170, v168
	v_mul_f32_e32 v208, v208, v206
	v_mul_f32_e32 v214, v214, v212
	v_mul_f32_e32 v220, v220, v218
	s_cbranch_vccnz .Lscan2_far3
.Lscan2_back3:
	v_sqrt_f32_e32 v170, v170
	v_sqrt_f32_e32 v208, v208
	v_sqrt_f32_e32 v214, v214
	v_sqrt_f32_e32 v220, v220
	v_mul_f32_e32 v167, v167, v170
	v_mul_f32_e32 v205, v205, v208
	v_mul_f32_e32 v211, v211, v214
	v_mul_f32_e32 v217, v217, v220
	ds_read_b128 v[150:153], v230 offset:256
	ds_read_b128 v[154:157], v230 offset:640
	ds_read_b128 v[158:161], v230 offset:1024
	ds_read_b128 v[162:165], v231 offset:256
	s_waitcnt lgkmcnt(0)
	v_mfma_f32_16x16x32_bf16 v[134:137], v[110:113], v[98:101], 0
	v_mfma_f32_16x16x32_bf16 v[138:141], v[122:125], v[98:101], 0
	v_mfma_f32_16x16x32_bf16 v[134:137], v[114:117], v[102:105], v[134:137]
	v_mfma_f32_16x16x32_bf16 v[138:141], v[126:129], v[102:105], v[138:141]
	v_mfma_f32_16x16x32_bf16 v[134:137], v[118:121], v[106:109], v[134:137]
	v_mfma_f32_16x16x32_bf16 v[138:141], v[130:133], v[106:109], v[138:141]
	v_fmac_f32_dpp v167, v167, v166 row_shr:1 row_mask:0xf bank_mask:0xf bound_ctrl:1
	v_fmac_f32_dpp v205, v205, v204 row_shr:1 row_mask:0xf bank_mask:0xf bound_ctrl:1
	v_fmac_f32_dpp v211, v211, v210 row_shr:1 row_mask:0xf bank_mask:0xf bound_ctrl:1
	v_fmac_f32_dpp v217, v217, v216 row_shr:1 row_mask:0xf bank_mask:0xf bound_ctrl:1
	v_mul_f32_dpp v166, v166, v166 row_shr:1 row_mask:0xf bank_mask:0xf
	v_mul_f32_dpp v204, v204, v204 row_shr:1 row_mask:0xf bank_mask:0xf
	v_mul_f32_dpp v210, v210, v210 row_shr:1 row_mask:0xf bank_mask:0xf
	v_mul_f32_dpp v216, v216, v216 row_shr:1 row_mask:0xf bank_mask:0xf
	v_fmac_f32_dpp v167, v167, v166 row_shr:2 row_mask:0xf bank_mask:0xf bound_ctrl:1
	v_fmac_f32_dpp v205, v205, v204 row_shr:2 row_mask:0xf bank_mask:0xf bound_ctrl:1
	v_fmac_f32_dpp v211, v211, v210 row_shr:2 row_mask:0xf bank_mask:0xf bound_ctrl:1
	v_fmac_f32_dpp v217, v217, v216 row_shr:2 row_mask:0xf bank_mask:0xf bound_ctrl:1
	v_mul_f32_dpp v166, v166, v166 row_shr:2 row_mask:0xf bank_mask:0xf
	v_mul_f32_dpp v204, v204, v204 row_shr:2 row_mask:0xf bank_mask:0xf
	v_mul_f32_dpp v210, v210, v210 row_shr:2 row_mask:0xf bank_mask:0xf
	v_mul_f32_dpp v216, v216, v216 row_shr:2 row_mask:0xf bank_mask:0xf
	v_fmac_f32_dpp v167, v167, v166 row_shr:4 row_mask:0xf bank_mask:0xf bound_ctrl:1
	v_fmac_f32_dpp v205, v205, v204 row_shr:4 row_mask:0xf bank_mask:0xf bound_ctrl:1
	v_fmac_f32_dpp v211, v211, v210 row_shr:4 row_mask:0xf bank_mask:0xf bound_ctrl:1
	v_fmac_f32_dpp v217, v217, v216 row_shr:4 row_mask:0xf bank_mask:0xf bound_ctrl:1
	v_mul_f32_dpp v166, v166, v166 row_shr:4 row_mask:0xf bank_mask:0xf
	v_mul_f32_dpp v204, v204, v204 row_shr:4 row_mask:0xf bank_mask:0xf
	v_mul_f32_dpp v210, v210, v210 row_shr:4 row_mask:0xf bank_mask:0xf
	v_mul_f32_dpp v216, v216, v216 row_shr:4 row_mask:0xf bank_mask:0xf
	v_fmac_f32_dpp v167, v167, v166 row_shr:8 row_mask:0xf bank_mask:0xf bound_ctrl:1
	v_fmac_f32_dpp v205, v205, v204 row_shr:8 row_mask:0xf bank_mask:0xf bound_ctrl:1
	v_fmac_f32_dpp v211, v211, v210 row_shr:8 row_mask:0xf bank_mask:0xf bound_ctrl:1
	v_fmac_f32_dpp v217, v217, v216 row_shr:8 row_mask:0xf bank_mask:0xf bound_ctrl:1
	v_mul_f32_dpp v166, v166, v166 row_shr:8 row_mask:0xf bank_mask:0xf
	v_mul_f32_dpp v204, v204, v204 row_shr:8 row_mask:0xf bank_mask:0xf
	v_mul_f32_dpp v210, v210, v210 row_shr:8 row_mask:0xf bank_mask:0xf
	v_mul_f32_dpp v216, v216, v216 row_shr:8 row_mask:0xf bank_mask:0xf
	v_fma_f32 v168, v166, v12, v167
	v_fma_f32 v206, v204, v13, v205
	v_fma_f32 v212, v210, v14, v211
	v_fma_f32 v218, v216, v15, v217
	ds_bpermute_b32 v12, v232, v168
	ds_bpermute_b32 v13, v232, v206
	ds_bpermute_b32 v14, v232, v212
	ds_bpermute_b32 v15, v232, v218
	s_waitcnt vmcnt(21)
	v_lshlrev_b32_e32 v169, 16, v30
	v_and_b32_e32 v207, 0xffff0000, v30
	v_lshlrev_b32_e32 v213, 16, v31
	v_and_b32_e32 v219, 0xffff0000, v31
	v_mul_f32_e32 v170, v169, v169
	v_mul_f32_e32 v208, v207, v207
	v_mul_f32_e32 v214, v213, v213
	v_mul_f32_e32 v220, v219, v219
	v_fmaak_f32 v170, v170, v249, 0xc0135761
	v_fmaak_f32 v208, v208, v249, 0xc0135761
	v_fmaak_f32 v214, v214, v249, 0xc0135761
	v_fmaak_f32 v220, v220, v249, 0xc0135761
	v_mul_f32_e32 v170, v169, v170
	v_mul_f32_e32 v208, v207, v208
	v_mul_f32_e32 v214, v213, v214
	v_mul_f32_e32 v220, v219, v220
	v_exp_f32_e32 v170, v170
	v_exp_f32_e32 v208, v208
	v_exp_f32_e32 v214, v214
	v_exp_f32_e32 v220, v220
	v_add_f32_e32 v170, 1.0, v170
	v_add_f32_e32 v208, 1.0, v208
	v_add_f32_e32 v214, 1.0, v214
	v_add_f32_e32 v220, 1.0, v220
	v_rcp_f32_e32 v170, v170
	v_rcp_f32_e32 v208, v208
	v_rcp_f32_e32 v214, v214
	v_rcp_f32_e32 v220, v220
	v_mul_f32_e32 v170, v169, v170
	v_mul_f32_e32 v208, v207, v208
	v_mul_f32_e32 v214, v213, v214
	v_mul_f32_e32 v220, v219, v220
	v_mul_f32_e32 v170, v170, v168
	v_mul_f32_e32 v208, v208, v206
	v_mul_f32_e32 v214, v214, v212
	v_mul_f32_e32 v220, v220, v218
	v_cvt_pk_bf16_f32 v242, v170, v208
	v_cvt_pk_bf16_f32 v243, v214, v220
	global_store_dwordx2 v236, v[242:243], s[100:101] offset:96
	ds_read_b128 v[110:113], v229 offset:16640
	ds_read_b128 v[122:125], v229 offset:36608
	ds_read_b128 v[114:117], v229 offset:16704
	ds_read_b128 v[126:129], v229 offset:36672
	ds_read_b128 v[118:121], v229 offset:16768
	ds_read_b128 v[130:133], v229 offset:36736
	v_fmamk_f32 v166, v134, 0xbfb8aa3b, v150
	v_fmamk_f32 v204, v135, 0xbfb8aa3b, v151
	v_fmamk_f32 v210, v136, 0xbfb8aa3b, v152
	v_fmamk_f32 v216, v137, 0xbfb8aa3b, v153
	v_fmamk_f32 v167, v138, 0xbfb8aa3b, v154
	v_fmamk_f32 v205, v139, 0xbfb8aa3b, v155
	v_fmamk_f32 v211, v140, 0xbfb8aa3b, v156
	v_fmamk_f32 v217, v141, 0xbfb8aa3b, v157
	v_exp_f32_e32 v166, v166
	v_exp_f32_e32 v204, v204
	v_exp_f32_e32 v210, v210
	v_exp_f32_e32 v216, v216
	v_exp_f32_e32 v167, v167
	v_exp_f32_e32 v205, v205
	v_exp_f32_e32 v211, v211
	v_exp_f32_e32 v217, v217
	v_add_f32_e32 v166, 1.0, v166
	v_add_f32_e32 v204, 1.0, v204
	v_add_f32_e32 v210, 1.0, v210
	v_add_f32_e32 v216, 1.0, v216
	v_add_f32_e32 v167, 1.0, v167
	v_add_f32_e32 v205, 1.0, v205
	v_add_f32_e32 v211, 1.0, v211
	v_add_f32_e32 v217, 1.0, v217
	v_rcp_f32_e32 v166, v166
	v_rcp_f32_e32 v204, v204
	v_rcp_f32_e32 v210, v210
	v_rcp_f32_e32 v216, v216
	v_rcp_f32_e32 v167, v167
	v_rcp_f32_e32 v205, v205
	v_rcp_f32_e32 v211, v211
	v_rcp_f32_e32 v217, v217
	v_mul_f32_e32 v168, v158, v166
	v_mul_f32_e32 v206, v159, v204
	v_mul_f32_e32 v212, v160, v210
	v_mul_f32_e32 v218, v161, v216
	v_mul_f32_e32 v167, v162, v167
	v_mul_f32_e32 v205, v163, v205
	v_mul_f32_e32 v211, v164, v211
	v_mul_f32_e32 v217, v165, v217
	v_exp_f32_e32 v166, v168
	v_exp_f32_e32 v204, v206
	v_exp_f32_e32 v210, v212
	v_exp_f32_e32 v216, v218
	v_fmaak_f32 v170, v168, v248, 0xbe1d955b
	v_fmaak_f32 v208, v206, v248, 0xbe1d955b
	v_fmaak_f32 v214, v212, v248, 0xbe1d955b
	v_fmaak_f32 v220, v218, v248, 0xbe1d955b
	v_fmaak_f32 v170, v168, v170, 0xbee35847
	v_fmaak_f32 v208, v206, v208, 0xbee35847
	v_fmaak_f32 v214, v212, v214, 0xbee35847
	v_fmaak_f32 v220, v218, v220, 0xbee35847
	v_min3_f32 v169, v168, v206, v212
	v_fmaak_f32 v170, v168, v170, 0xbf75fdf0
	v_fmaak_f32 v208, v206, v208, 0xbf75fdf0
	v_fmaak_f32 v214, v212, v214, 0xbf75fdf0
	v_fmaak_f32 v220, v218, v220, 0xbf75fdf0
	v_min_f32_e32 v169, v169, v218
	v_fmaak_f32 v170, v168, v170, 0xbfb17218
	v_fmaak_f32 v208, v206, v208, 0xbfb17218
	v_fmaak_f32 v214, v212, v214, 0xbfb17218
	v_fmaak_f32 v220, v218, v220, 0xbfb17218
	v_cmp_nlt_f32_e32 vcc, 0xbe38aa3b, v169
	v_mul_f32_e32 v170, v170, v168
	v_mul_f32_e32 v208, v208, v206
	v_mul_f32_e32 v214, v214, v212
	v_mul_f32_e32 v220, v220, v218
	s_cbranch_vccnz .Lscan2_far4
.Lscan2_back4:
	v_sqrt_f32_e32 v170, v170
	v_sqrt_f32_e32 v208, v208
	v_sqrt_f32_e32 v214, v214
	v_sqrt_f32_e32 v220, v220
	v_mul_f32_e32 v167, v167, v170
	v_mul_f32_e32 v205, v205, v208
	v_mul_f32_e32 v211, v211, v214
	v_mul_f32_e32 v217, v217, v220
	ds_read_b128 v[150:153], v230 offset:320
	ds_read_b128 v[154:157], v230 offset:704
	ds_read_b128 v[158:161], v230 offset:1088
	ds_read_b128 v[162:165], v231 offset:320
	s_waitcnt lgkmcnt(0)
	v_mfma_f32_16x16x32_bf16 v[142:145], v[110:113], v[98:101], 0
	v_mfma_f32_16x16x32_bf16 v[146:149], v[122:125], v[98:101], 0
	v_mfma_f32_16x16x32_bf16 v[142:145], v[114:117], v[102:105], v[142:145]
	v_mfma_f32_16x16x32_bf16 v[146:149], v[126:129], v[102:105], v[146:149]
	v_mfma_f32_16x16x32_bf16 v[142:145], v[118:121], v[106:109], v[142:145]
	v_mfma_f32_16x16x32_bf16 v[146:149], v[130:133], v[106:109], v[146:149]
	v_fmac_f32_dpp v167, v167, v166 row_shr:1 row_mask:0xf bank_mask:0xf bound_ctrl:1
	v_fmac_f32_dpp v205, v205, v204 row_shr:1 row_mask:0xf bank_mask:0xf bound_ctrl:1
	v_fmac_f32_dpp v211, v211, v210 row_shr:1 row_mask:0xf bank_mask:0xf bound_ctrl:1
	v_fmac_f32_dpp v217, v217, v216 row_shr:1 row_mask:0xf bank_mask:0xf bound_ctrl:1
	v_mul_f32_dpp v166, v166, v166 row_shr:1 row_mask:0xf bank_mask:0xf
	v_mul_f32_dpp v204, v204, v204 row_shr:1 row_mask:0xf bank_mask:0xf
	v_mul_f32_dpp v210, v210, v210 row_shr:1 row_mask:0xf bank_mask:0xf
	v_mul_f32_dpp v216, v216, v216 row_shr:1 row_mask:0xf bank_mask:0xf
	v_fmac_f32_dpp v167, v167, v166 row_shr:2 row_mask:0xf bank_mask:0xf bound_ctrl:1
	v_fmac_f32_dpp v205, v205, v204 row_shr:2 row_mask:0xf bank_mask:0xf bound_ctrl:1
	v_fmac_f32_dpp v211, v211, v210 row_shr:2 row_mask:0xf bank_mask:0xf bound_ctrl:1
	v_fmac_f32_dpp v217, v217, v216 row_shr:2 row_mask:0xf bank_mask:0xf bound_ctrl:1
	v_mul_f32_dpp v166, v166, v166 row_shr:2 row_mask:0xf bank_mask:0xf
	v_mul_f32_dpp v204, v204, v204 row_shr:2 row_mask:0xf bank_mask:0xf
	v_mul_f32_dpp v210, v210, v210 row_shr:2 row_mask:0xf bank_mask:0xf
	v_mul_f32_dpp v216, v216, v216 row_shr:2 row_mask:0xf bank_mask:0xf
	v_fmac_f32_dpp v167, v167, v166 row_shr:4 row_mask:0xf bank_mask:0xf bound_ctrl:1
	v_fmac_f32_dpp v205, v205, v204 row_shr:4 row_mask:0xf bank_mask:0xf bound_ctrl:1
	v_fmac_f32_dpp v211, v211, v210 row_shr:4 row_mask:0xf bank_mask:0xf bound_ctrl:1
	v_fmac_f32_dpp v217, v217, v216 row_shr:4 row_mask:0xf bank_mask:0xf bound_ctrl:1
	v_mul_f32_dpp v166, v166, v166 row_shr:4 row_mask:0xf bank_mask:0xf
	v_mul_f32_dpp v204, v204, v204 row_shr:4 row_mask:0xf bank_mask:0xf
	v_mul_f32_dpp v210, v210, v210 row_shr:4 row_mask:0xf bank_mask:0xf
	v_mul_f32_dpp v216, v216, v216 row_shr:4 row_mask:0xf bank_mask:0xf
	v_fmac_f32_dpp v167, v167, v166 row_shr:8 row_mask:0xf bank_mask:0xf bound_ctrl:1
	v_fmac_f32_dpp v205, v205, v204 row_shr:8 row_mask:0xf bank_mask:0xf bound_ctrl:1
	v_fmac_f32_dpp v211, v211, v210 row_shr:8 row_mask:0xf bank_mask:0xf bound_ctrl:1
	v_fmac_f32_dpp v217, v217, v216 row_shr:8 row_mask:0xf bank_mask:0xf bound_ctrl:1
	v_mul_f32_dpp v166, v166, v166 row_shr:8 row_mask:0xf bank_mask:0xf
	v_mul_f32_dpp v204, v204, v204 row_shr:8 row_mask:0xf bank_mask:0xf
	v_mul_f32_dpp v210, v210, v210 row_shr:8 row_mask:0xf bank_mask:0xf
	v_mul_f32_dpp v216, v216, v216 row_shr:8 row_mask:0xf bank_mask:0xf
	v_fma_f32 v168, v166, v16, v167
	v_fma_f32 v206, v204, v17, v205
	v_fma_f32 v212, v210, v18, v211
	v_fma_f32 v218, v216, v19, v217
	ds_bpermute_b32 v16, v232, v168
	ds_bpermute_b32 v17, v232, v206
	ds_bpermute_b32 v18, v232, v212
	ds_bpermute_b32 v19, v232, v218
	s_waitcnt vmcnt(21)
	v_lshlrev_b32_e32 v169, 16, v32
	v_and_b32_e32 v207, 0xffff0000, v32
	v_lshlrev_b32_e32 v213, 16, v33
	v_and_b32_e32 v219, 0xffff0000, v33
	v_mul_f32_e32 v170, v169, v169
	v_mul_f32_e32 v208, v207, v207
	v_mul_f32_e32 v214, v213, v213
	v_mul_f32_e32 v220, v219, v219
	v_fmaak_f32 v170, v170, v249, 0xc0135761
	v_fmaak_f32 v208, v208, v249, 0xc0135761
	v_fmaak_f32 v214, v214, v249, 0xc0135761
	v_fmaak_f32 v220, v220, v249, 0xc0135761
	v_mul_f32_e32 v170, v169, v170
	v_mul_f32_e32 v208, v207, v208
	v_mul_f32_e32 v214, v213, v214
	v_mul_f32_e32 v220, v219, v220
	v_exp_f32_e32 v170, v170
	v_exp_f32_e32 v208, v208
	v_exp_f32_e32 v214, v214
	v_exp_f32_e32 v220, v220
	v_add_f32_e32 v170, 1.0, v170
	v_add_f32_e32 v208, 1.0, v208
	v_add_f32_e32 v214, 1.0, v214
	v_add_f32_e32 v220, 1.0, v220
	v_rcp_f32_e32 v170, v170
	v_rcp_f32_e32 v208, v208
	v_rcp_f32_e32 v214, v214
	v_rcp_f32_e32 v220, v220
	v_mul_f32_e32 v170, v169, v170
	v_mul_f32_e32 v208, v207, v208
	v_mul_f32_e32 v214, v213, v214
	v_mul_f32_e32 v220, v219, v220
	v_mul_f32_e32 v170, v170, v168
	v_mul_f32_e32 v208, v208, v206
	v_mul_f32_e32 v214, v214, v212
	v_mul_f32_e32 v220, v220, v218
	v_cvt_pk_bf16_f32 v242, v170, v208
	v_cvt_pk_bf16_f32 v243, v214, v220
	global_store_dwordx2 v236, v[242:243], s[100:101] offset:128
	v_fmamk_f32 v166, v142, 0xbfb8aa3b, v150
	v_fmamk_f32 v204, v143, 0xbfb8aa3b, v151
	v_fmamk_f32 v210, v144, 0xbfb8aa3b, v152
	v_fmamk_f32 v216, v145, 0xbfb8aa3b, v153
	v_fmamk_f32 v167, v146, 0xbfb8aa3b, v154
	v_fmamk_f32 v205, v147, 0xbfb8aa3b, v155
	v_fmamk_f32 v211, v148, 0xbfb8aa3b, v156
	v_fmamk_f32 v217, v149, 0xbfb8aa3b, v157
	v_exp_f32_e32 v166, v166
	v_exp_f32_e32 v204, v204
	v_exp_f32_e32 v210, v210
	v_exp_f32_e32 v216, v216
	v_exp_f32_e32 v167, v167
	v_exp_f32_e32 v205, v205
	v_exp_f32_e32 v211, v211
	v_exp_f32_e32 v217, v217
	v_add_f32_e32 v166, 1.0, v166
	v_add_f32_e32 v204, 1.0, v204
	v_add_f32_e32 v210, 1.0, v210
	v_add_f32_e32 v216, 1.0, v216
	v_add_f32_e32 v167, 1.0, v167
	v_add_f32_e32 v205, 1.0, v205
	v_add_f32_e32 v211, 1.0, v211
	v_add_f32_e32 v217, 1.0, v217
	v_rcp_f32_e32 v166, v166
	v_rcp_f32_e32 v204, v204
	v_rcp_f32_e32 v210, v210
	v_rcp_f32_e32 v216, v216
	v_rcp_f32_e32 v167, v167
	v_rcp_f32_e32 v205, v205
	v_rcp_f32_e32 v211, v211
	v_rcp_f32_e32 v217, v217
	v_mul_f32_e32 v168, v158, v166
	v_mul_f32_e32 v206, v159, v204
	v_mul_f32_e32 v212, v160, v210
	v_mul_f32_e32 v218, v161, v216
	v_mul_f32_e32 v167, v162, v167
	v_mul_f32_e32 v205, v163, v205
	v_mul_f32_e32 v211, v164, v211
	v_mul_f32_e32 v217, v165, v217
	v_exp_f32_e32 v166, v168
	v_exp_f32_e32 v204, v206
	v_exp_f32_e32 v210, v212
	v_exp_f32_e32 v216, v218
	v_fmaak_f32 v170, v168, v248, 0xbe1d955b
	v_fmaak_f32 v208, v206, v248, 0xbe1d955b
	v_fmaak_f32 v214, v212, v248, 0xbe1d955b
	v_fmaak_f32 v220, v218, v248, 0xbe1d955b
	v_fmaak_f32 v170, v168, v170, 0xbee35847
	v_fmaak_f32 v208, v206, v208, 0xbee35847
	v_fmaak_f32 v214, v212, v214, 0xbee35847
	v_fmaak_f32 v220, v218, v220, 0xbee35847
	v_min3_f32 v169, v168, v206, v212
	v_fmaak_f32 v170, v168, v170, 0xbf75fdf0
	v_fmaak_f32 v208, v206, v208, 0xbf75fdf0
	v_fmaak_f32 v214, v212, v214, 0xbf75fdf0
	v_fmaak_f32 v220, v218, v220, 0xbf75fdf0
	v_min_f32_e32 v169, v169, v218
	v_fmaak_f32 v170, v168, v170, 0xbfb17218
	v_fmaak_f32 v208, v206, v208, 0xbfb17218
	v_fmaak_f32 v214, v212, v214, 0xbfb17218
	v_fmaak_f32 v220, v218, v220, 0xbfb17218
	v_cmp_nlt_f32_e32 vcc, 0xbe38aa3b, v169
	v_mul_f32_e32 v170, v170, v168
	v_mul_f32_e32 v208, v208, v206
	v_mul_f32_e32 v214, v214, v212
	v_mul_f32_e32 v220, v220, v218
	s_cbranch_vccnz .Lscan2_far5
.Lscan2_back5:
	v_sqrt_f32_e32 v170, v170
	v_sqrt_f32_e32 v208, v208
	v_sqrt_f32_e32 v214, v214
	v_sqrt_f32_e32 v220, v220
	v_mul_f32_e32 v167, v167, v170
	v_mul_f32_e32 v205, v205, v208
	v_mul_f32_e32 v211, v211, v214
	v_mul_f32_e32 v217, v217, v220
	s_waitcnt lgkmcnt(0)
	v_fmac_f32_dpp v167, v167, v166 row_shr:1 row_mask:0xf bank_mask:0xf bound_ctrl:1
	v_fmac_f32_dpp v205, v205, v204 row_shr:1 row_mask:0xf bank_mask:0xf bound_ctrl:1
	v_fmac_f32_dpp v211, v211, v210 row_shr:1 row_mask:0xf bank_mask:0xf bound_ctrl:1
	v_fmac_f32_dpp v217, v217, v216 row_shr:1 row_mask:0xf bank_mask:0xf bound_ctrl:1
	v_mul_f32_dpp v166, v166, v166 row_shr:1 row_mask:0xf bank_mask:0xf
	v_mul_f32_dpp v204, v204, v204 row_shr:1 row_mask:0xf bank_mask:0xf
	v_mul_f32_dpp v210, v210, v210 row_shr:1 row_mask:0xf bank_mask:0xf
	v_mul_f32_dpp v216, v216, v216 row_shr:1 row_mask:0xf bank_mask:0xf
	v_fmac_f32_dpp v167, v167, v166 row_shr:2 row_mask:0xf bank_mask:0xf bound_ctrl:1
	v_fmac_f32_dpp v205, v205, v204 row_shr:2 row_mask:0xf bank_mask:0xf bound_ctrl:1
	v_fmac_f32_dpp v211, v211, v210 row_shr:2 row_mask:0xf bank_mask:0xf bound_ctrl:1
	v_fmac_f32_dpp v217, v217, v216 row_shr:2 row_mask:0xf bank_mask:0xf bound_ctrl:1
	v_mul_f32_dpp v166, v166, v166 row_shr:2 row_mask:0xf bank_mask:0xf
	v_mul_f32_dpp v204, v204, v204 row_shr:2 row_mask:0xf bank_mask:0xf
	v_mul_f32_dpp v210, v210, v210 row_shr:2 row_mask:0xf bank_mask:0xf
	v_mul_f32_dpp v216, v216, v216 row_shr:2 row_mask:0xf bank_mask:0xf
	v_fmac_f32_dpp v167, v167, v166 row_shr:4 row_mask:0xf bank_mask:0xf bound_ctrl:1
	v_fmac_f32_dpp v205, v205, v204 row_shr:4 row_mask:0xf bank_mask:0xf bound_ctrl:1
	v_fmac_f32_dpp v211, v211, v210 row_shr:4 row_mask:0xf bank_mask:0xf bound_ctrl:1
	v_fmac_f32_dpp v217, v217, v216 row_shr:4 row_mask:0xf bank_mask:0xf bound_ctrl:1
	v_mul_f32_dpp v166, v166, v166 row_shr:4 row_mask:0xf bank_mask:0xf
	v_mul_f32_dpp v204, v204, v204 row_shr:4 row_mask:0xf bank_mask:0xf
	v_mul_f32_dpp v210, v210, v210 row_shr:4 row_mask:0xf bank_mask:0xf
	v_mul_f32_dpp v216, v216, v216 row_shr:4 row_mask:0xf bank_mask:0xf
	v_fmac_f32_dpp v167, v167, v166 row_shr:8 row_mask:0xf bank_mask:0xf bound_ctrl:1
	v_fmac_f32_dpp v205, v205, v204 row_shr:8 row_mask:0xf bank_mask:0xf bound_ctrl:1
	v_fmac_f32_dpp v211, v211, v210 row_shr:8 row_mask:0xf bank_mask:0xf bound_ctrl:1
	v_fmac_f32_dpp v217, v217, v216 row_shr:8 row_mask:0xf bank_mask:0xf bound_ctrl:1
	v_mul_f32_dpp v166, v166, v166 row_shr:8 row_mask:0xf bank_mask:0xf
	v_mul_f32_dpp v204, v204, v204 row_shr:8 row_mask:0xf bank_mask:0xf
	v_mul_f32_dpp v210, v210, v210 row_shr:8 row_mask:0xf bank_mask:0xf
	v_mul_f32_dpp v216, v216, v216 row_shr:8 row_mask:0xf bank_mask:0xf
	v_fma_f32 v168, v166, v20, v167
	v_fma_f32 v206, v204, v21, v205
	v_fma_f32 v212, v210, v22, v211
	v_fma_f32 v218, v216, v23, v217
	ds_bpermute_b32 v20, v232, v168
	ds_bpermute_b32 v21, v232, v206
	ds_bpermute_b32 v22, v232, v212
	ds_bpermute_b32 v23, v232, v218
	s_waitcnt vmcnt(21)
	v_lshlrev_b32_e32 v169, 16, v34
	v_and_b32_e32 v207, 0xffff0000, v34
	v_lshlrev_b32_e32 v213, 16, v35
	v_and_b32_e32 v219, 0xffff0000, v35
	v_mul_f32_e32 v170, v169, v169
	v_mul_f32_e32 v208, v207, v207
	v_mul_f32_e32 v214, v213, v213
	v_mul_f32_e32 v220, v219, v219
	v_fmaak_f32 v170, v170, v249, 0xc0135761
	v_fmaak_f32 v208, v208, v249, 0xc0135761
	v_fmaak_f32 v214, v214, v249, 0xc0135761
	v_fmaak_f32 v220, v220, v249, 0xc0135761
	v_mul_f32_e32 v170, v169, v170
	v_mul_f32_e32 v208, v207, v208
	v_mul_f32_e32 v214, v213, v214
	v_mul_f32_e32 v220, v219, v220
	v_exp_f32_e32 v170, v170
	v_exp_f32_e32 v208, v208
	v_exp_f32_e32 v214, v214
	v_exp_f32_e32 v220, v220
	v_add_f32_e32 v170, 1.0, v170
	v_add_f32_e32 v208, 1.0, v208
	v_add_f32_e32 v214, 1.0, v214
	v_add_f32_e32 v220, 1.0, v220
	v_rcp_f32_e32 v170, v170
	v_rcp_f32_e32 v208, v208
	v_rcp_f32_e32 v214, v214
	v_rcp_f32_e32 v220, v220
	v_mul_f32_e32 v170, v169, v170
	v_mul_f32_e32 v208, v207, v208
	v_mul_f32_e32 v214, v213, v214
	v_mul_f32_e32 v220, v219, v220
	v_mul_f32_e32 v170, v170, v168
	v_mul_f32_e32 v208, v208, v206
	v_mul_f32_e32 v214, v214, v212
	v_mul_f32_e32 v220, v220, v218
	v_cvt_pk_bf16_f32 v242, v170, v208
	v_cvt_pk_bf16_f32 v243, v214, v220
	global_store_dwordx2 v236, v[242:243], s[100:101] offset:160
	s_waitcnt lgkmcnt(0)
	s_waitcnt vmcnt(6)
	v_mov_b32_e32 v66, v82
	v_mov_b32_e32 v67, v83
	v_mov_b32_e32 v68, v84
	v_mov_b32_e32 v69, v85
	v_mov_b32_e32 v70, v86
	v_mov_b32_e32 v71, v87
	v_mov_b32_e32 v72, v88
	v_mov_b32_e32 v73, v89
	v_mov_b32_e32 v74, v90
	v_mov_b32_e32 v75, v91
	v_mov_b32_e32 v76, v92
	v_mov_b32_e32 v77, v93
	v_mov_b32_e32 v78, v94
	v_mov_b32_e32 v79, v95
	v_mov_b32_e32 v80, v96
	v_mov_b32_e32 v81, v97
	s_add_u32 s6, s6, 0x18000
	s_addc_u32 s7, s7, 0
	s_add_u32 s100, s100, 0xc000
	s_addc_u32 s101, s101, 0
	s_add_i32 s64, s64, 1
	s_cmp_lt_u32 s64, 3
	s_cbranch_scc1 .Lscan2_sub
	s_add_i32 s23, s23, s42

.Lscan2_end:
.LBB0_548:
	v_readlane_b32 s4, v254, 4
	s_add_i32 s0, s87, 4
	v_readlane_b32 s5, v254, 5
	s_cmp_ge_i32 s0, s5
	s_cbranch_scc1 .LBB0_560
	s_cmp_lg_u32 s36, 0
	s_mov_b32 s20, s66
	s_cbranch_scc0 .LBB0_561
	v_mov_b32_e32 v0, v192
	s_add_i32 s10, s60, 1
	s_waitcnt vmcnt(0) lgkmcnt(0)
	s_barrier
	s_nop 0
	v_cmp_eq_u32_e32 vcc, 0, v0
	s_and_saveexec_b64 s[4:5], vcc
	s_cbranch_execz .LBB0_559
	s_mov_b64 s[8:9], exec
	v_mbcnt_lo_u32_b32 v0, s8, 0
	v_mbcnt_hi_u32_b32 v0, s9, v0
	v_cmp_eq_u32_e32 vcc, 0, v0
	buffer_wbl2 sc1
	s_and_saveexec_b64 s[6:7], vcc
	s_cbranch_execz .LBB0_553
	v_readlane_b32 s11, v254, 18
	s_lshl_b32 s11, s11, 2
	s_bcnt1_i32_b64 s8, s[8:9]
	v_mov_b32_e32 v1, s11
	v_mov_b32_e32 v2, s8
	global_atomic_add v1, v1, v2, s[14:15] offset:256 sc0
